# SG epilogue + K-loop load batching, queue ticket prefetch, NA bias de-serialisation, SG row-loop batching, static wave priorities, P0 GEMV pipelining
# baseline (speedup 1.0000x reference)
; __device__ __forceinline__ int opaque_tid() { int t; asm volatile("v_mov_b32 %0, %1" : "=v"(t) : "v"((int)threadIdx.x)); return t; }
; #define ws (opq(P.ws))
; __device__ __forceinline__ void sg_unit(const Params& P, int l, int chunk, char* shm, float* ssb) {
;     const int tid_ = opaque_tid(), lane = tid_ & 63, wid = __builtin_amdgcn_readfirstlane(tid_ >> 6);
;     unsigned char* ws = P.ws;
;     const bf16_t* qkv = (const bf16_t*)(ws + WS_QKV); bf16_t* omix = (bf16_t*)(ws + WS_OMIX);
;     const bf16_t* Wsb = (const bf16_t*)(ws + WS_WS) + (size_t)l * 4 * 128 * 128;
;     const int R0 = chunk * 128;
;     bf16_t* vt = (bf16_t*)(shm + SG_VT);
;     const float* gs = P.g_sgu + l * 256;
;     const f32x4 g4 = *(const f32x4*)(gs + 4 * lane);
;     for (int q = wid * 16; q < wid * 16 + 16; ++q) {
;         const u32x2 vv = *(const u32x2*)(qkv + (size_t)(R0 + q) * DIN + C_V + 4 * lane);
;         f32x4 v; v[0] = __uint_as_float(vv.x << 16); v[1] = __uint_as_float(vv.x & 0xffff0000u); v[2] = __uint_as_float(vv.y << 16); v[3] = __uint_as_float(vv.y & 0xffff0000u);
.LBB0_556:
	s_andn2_b64 vcc, exec, s[0:1]
	s_cbranch_vccnz .LBB0_579
	s_add_i32 s3, s48, 0xfffffd00
	s_add_i32 s0, s48, 0xfffffcbe
	s_cmpk_lt_u32 s3, 0x42
	s_cselect_b32 s0, s3, s0
	s_cmp_lt_u32 s0, 64
	v_readlane_b32 s4, v252, 11
	s_cselect_b64 s[0:1], -1, 0
	v_readlane_b32 s5, v252, 12
	s_or_b64 s[0:1], s[4:5], s[0:1]
	s_andn2_b64 vcc, exec, s[0:1]
	s_cbranch_vccnz .LBB0_579
	s_mov_b64 s[4:5], s[76:77]
	v_mov_b32 v12, v214
	v_readlane_b32 s0, v252, 18
	v_and_b32_e32 v13, 63, v12
	v_lshlrev_b32_e32 v0, 4, v13
	v_readlane_b32 s1, v252, 19
	v_xor_b32_e32 v6, 1, v220
	v_readfirstlane_b32 s6, v12
	s_ashr_i32 s2, s6, 6
	v_readlane_b32 s8, v254, 36
	s_mov_b32 s7, 0
	global_load_dwordx4 v[2:5], v0, s[0:1]
	v_and_b32_e32 v0, 64, v220
	v_add_u32_e32 v0, 64, v0
	v_cmp_lt_i32_e32 vcc, v6, v0
	s_lshl_b32 s1, s2, 5
	s_add_i32 s1, s1, 0
	v_cndmask_b32_e32 v6, v220, v6, vcc
	v_lshlrev_b32_e32 v17, 2, v6
	v_xor_b32_e32 v6, 2, v220
	v_cmp_lt_i32_e32 vcc, v6, v0
	s_lshl_b32 s0, s2, 4
	s_nop 0
	v_cndmask_b32_e32 v6, v220, v6, vcc
	v_lshlrev_b32_e32 v83, 2, v6
	v_xor_b32_e32 v6, 4, v220
	v_cmp_lt_i32_e32 vcc, v6, v0
	s_nop 1
	v_cndmask_b32_e32 v6, v220, v6, vcc
	v_lshlrev_b32_e32 v82, 2, v6
	v_xor_b32_e32 v6, 8, v220
	v_cmp_lt_i32_e32 vcc, v6, v0
	s_nop 1
	v_cndmask_b32_e32 v6, v220, v6, vcc
	v_lshlrev_b32_e32 v14, 2, v6
	v_xor_b32_e32 v6, 16, v220
	v_cmp_lt_i32_e32 vcc, v6, v0
	s_nop 1
	v_cndmask_b32_e32 v6, v220, v6, vcc
	v_lshlrev_b32_e32 v15, 2, v6
	v_xor_b32_e32 v6, 32, v220
	v_cmp_lt_i32_e32 vcc, v6, v0
	s_nop 1
	v_cndmask_b32_e32 v0, v220, v6, vcc
	v_lshlrev_b32_e32 v18, 2, v0
	v_mov_b32_e32 v0, s1
	s_movk_i32 s1, 0x440
	v_mad_u32_u24 v19, v13, s1, v0
	s_lshl_b32 s1, s48, 7
	s_add_i32 s0, s1, s0
	s_add_i32 s0, s0, 0xfffe8000
	s_mul_hi_i32 s1, s0, 0x1200
	s_mulk_i32 s0, 0x1200
	s_add_u32 s0, s8, s0
	v_readlane_b32 s8, v254, 37
	v_lshlrev_b32_e32 v0, 3, v13
	s_addc_u32 s1, s8, s1
	v_lshl_add_u64 v[6:7], s[0:1], 0, v[0:1]
	s_mov_b64 s[8:9], 0x1200
	global_load_dwordx2 v[96:97], v[6:7], off
	v_lshl_add_u64 v[6:7], v[6:7], 0, s[8:9]
	global_load_dwordx2 v[98:99], v[6:7], off
	v_lshl_add_u64 v[6:7], v[6:7], 0, s[8:9]
	global_load_dwordx2 v[100:101], v[6:7], off
	v_lshl_add_u64 v[6:7], v[6:7], 0, s[8:9]
	global_load_dwordx2 v[102:103], v[6:7], off
	v_lshl_add_u64 v[6:7], v[6:7], 0, s[8:9]
	global_load_dwordx2 v[104:105], v[6:7], off
	v_lshl_add_u64 v[6:7], v[6:7], 0, s[8:9]
	global_load_dwordx2 v[106:107], v[6:7], off
	v_lshl_add_u64 v[6:7], v[6:7], 0, s[8:9]
	global_load_dwordx2 v[108:109], v[6:7], off
	v_lshl_add_u64 v[6:7], v[6:7], 0, s[8:9]
	global_load_dwordx2 v[110:111], v[6:7], off
	v_lshl_add_u64 v[6:7], v[6:7], 0, s[8:9]
	global_load_dwordx2 v[112:113], v[6:7], off
	v_lshl_add_u64 v[6:7], v[6:7], 0, s[8:9]
	global_load_dwordx2 v[114:115], v[6:7], off
	v_lshl_add_u64 v[6:7], v[6:7], 0, s[8:9]
	global_load_dwordx2 v[116:117], v[6:7], off
	v_lshl_add_u64 v[6:7], v[6:7], 0, s[8:9]
	global_load_dwordx2 v[118:119], v[6:7], off
	v_lshl_add_u64 v[6:7], v[6:7], 0, s[8:9]
	global_load_dwordx2 v[120:121], v[6:7], off
	v_lshl_add_u64 v[6:7], v[6:7], 0, s[8:9]
	global_load_dwordx2 v[122:123], v[6:7], off
	v_lshl_add_u64 v[6:7], v[6:7], 0, s[8:9]
	global_load_dwordx2 v[124:125], v[6:7], off
	v_lshl_add_u64 v[6:7], v[6:7], 0, s[8:9]
	global_load_dwordx2 v[126:127], v[6:7], off
	s_waitcnt vmcnt(0)
	v_lshlrev_b32_e32 v130, 16, v97
	v_lshlrev_b32_e32 v128, 16, v96
	v_and_b32_e32 v131, 0xffff0000, v97
	v_and_b32_e32 v129, 0xffff0000, v96
	v_lshlrev_b32_e32 v134, 16, v99
	v_lshlrev_b32_e32 v132, 16, v98
	v_and_b32_e32 v135, 0xffff0000, v99
	v_and_b32_e32 v133, 0xffff0000, v98
	v_lshlrev_b32_e32 v138, 16, v101
	v_lshlrev_b32_e32 v136, 16, v100
	v_and_b32_e32 v139, 0xffff0000, v101
	v_and_b32_e32 v137, 0xffff0000, v100
	v_lshlrev_b32_e32 v142, 16, v103
	v_lshlrev_b32_e32 v140, 16, v102
	v_and_b32_e32 v143, 0xffff0000, v103
	v_and_b32_e32 v141, 0xffff0000, v102
	v_lshlrev_b32_e32 v146, 16, v105
	v_lshlrev_b32_e32 v144, 16, v104
	v_and_b32_e32 v147, 0xffff0000, v105
	v_and_b32_e32 v145, 0xffff0000, v104
	v_lshlrev_b32_e32 v150, 16, v107
	v_lshlrev_b32_e32 v148, 16, v106
	v_and_b32_e32 v151, 0xffff0000, v107
	v_and_b32_e32 v149, 0xffff0000, v106
	v_lshlrev_b32_e32 v154, 16, v109
	v_lshlrev_b32_e32 v152, 16, v108
	v_and_b32_e32 v155, 0xffff0000, v109
	v_and_b32_e32 v153, 0xffff0000, v108
	v_lshlrev_b32_e32 v158, 16, v111
	v_lshlrev_b32_e32 v156, 16, v110
	v_and_b32_e32 v159, 0xffff0000, v111
	v_and_b32_e32 v157, 0xffff0000, v110
	v_lshlrev_b32_e32 v162, 16, v113
	v_lshlrev_b32_e32 v160, 16, v112
	v_and_b32_e32 v163, 0xffff0000, v113
	v_and_b32_e32 v161, 0xffff0000, v112
	v_lshlrev_b32_e32 v166, 16, v115
	v_lshlrev_b32_e32 v164, 16, v114
	v_and_b32_e32 v167, 0xffff0000, v115
	v_and_b32_e32 v165, 0xffff0000, v114
	v_lshlrev_b32_e32 v170, 16, v117
	v_lshlrev_b32_e32 v168, 16, v116
	v_and_b32_e32 v171, 0xffff0000, v117
	v_and_b32_e32 v169, 0xffff0000, v116
	v_lshlrev_b32_e32 v174, 16, v119
	v_lshlrev_b32_e32 v172, 16, v118
	v_and_b32_e32 v175, 0xffff0000, v119
	v_and_b32_e32 v173, 0xffff0000, v118
	v_lshlrev_b32_e32 v178, 16, v121
	v_lshlrev_b32_e32 v176, 16, v120
	v_and_b32_e32 v179, 0xffff0000, v121
	v_and_b32_e32 v177, 0xffff0000, v120
	v_lshlrev_b32_e32 v182, 16, v123
	v_lshlrev_b32_e32 v180, 16, v122
	v_and_b32_e32 v183, 0xffff0000, v123
	v_and_b32_e32 v181, 0xffff0000, v122
	v_lshlrev_b32_e32 v186, 16, v125
	v_lshlrev_b32_e32 v184, 16, v124
	v_and_b32_e32 v187, 0xffff0000, v125
	v_and_b32_e32 v185, 0xffff0000, v124
	v_lshlrev_b32_e32 v190, 16, v127
	v_lshlrev_b32_e32 v188, 16, v126
	v_and_b32_e32 v191, 0xffff0000, v127
	v_and_b32_e32 v189, 0xffff0000, v126
; __device__ __forceinline__ float wave_sum(float v) {
; #pragma unroll
;     for (int o = 1; o < 64; o <<= 1) v += __shfl_xor(v, o);
;     return v;
; __device__ __forceinline__ void sg_unit(const Params& P, int l, int chunk, char* shm, float* ssb) {
;     ...
;         f32x4 v; v[0] = __uint_as_float(vv.x << 16); v[1] = __uint_as_float(vv.x & 0xffff0000u); v[2] = __uint_as_float(vv.y << 16); v[3] = __uint_as_float(vv.y & 0xffff0000u);
;         const float mean = wave_sum((v[0] + v[1]) + (v[2] + v[3])) * (1.f / 256.f);
	v_add_f32_e32 v208, v128, v129
	v_add_f32_e32 v209, v130, v131
	v_add_f32_e32 v192, v208, v209
	v_add_f32_e32 v208, v132, v133
	v_add_f32_e32 v209, v134, v135
	v_add_f32_e32 v193, v208, v209
	v_add_f32_e32 v208, v136, v137
	v_add_f32_e32 v209, v138, v139
	v_add_f32_e32 v194, v208, v209
	v_add_f32_e32 v208, v140, v141
	v_add_f32_e32 v209, v142, v143
	v_add_f32_e32 v195, v208, v209
	v_add_f32_e32 v208, v144, v145
	v_add_f32_e32 v209, v146, v147
	v_add_f32_e32 v196, v208, v209
	v_add_f32_e32 v208, v148, v149
	v_add_f32_e32 v209, v150, v151
	v_add_f32_e32 v197, v208, v209
	v_add_f32_e32 v208, v152, v153
	v_add_f32_e32 v209, v154, v155
	v_add_f32_e32 v198, v208, v209
	v_add_f32_e32 v208, v156, v157
	v_add_f32_e32 v209, v158, v159
	v_add_f32_e32 v199, v208, v209
	v_add_f32_e32 v208, v160, v161
	v_add_f32_e32 v209, v162, v163
	v_add_f32_e32 v200, v208, v209
	v_add_f32_e32 v208, v164, v165
	v_add_f32_e32 v209, v166, v167
	v_add_f32_e32 v201, v208, v209
	v_add_f32_e32 v208, v168, v169
	v_add_f32_e32 v209, v170, v171
	v_add_f32_e32 v202, v208, v209
	v_add_f32_e32 v208, v172, v173
	v_add_f32_e32 v209, v174, v175
	v_add_f32_e32 v203, v208, v209
	v_add_f32_e32 v208, v176, v177
	v_add_f32_e32 v209, v178, v179
	v_add_f32_e32 v204, v208, v209
	v_add_f32_e32 v208, v180, v181
	v_add_f32_e32 v209, v182, v183
	v_add_f32_e32 v205, v208, v209
	v_add_f32_e32 v208, v184, v185
	v_add_f32_e32 v209, v186, v187
	v_add_f32_e32 v206, v208, v209
	v_add_f32_e32 v208, v188, v189
	v_add_f32_e32 v209, v190, v191
	v_add_f32_e32 v207, v208, v209
	ds_bpermute_b32 v96, v17, v192
	ds_bpermute_b32 v97, v17, v193
	ds_bpermute_b32 v98, v17, v194
	ds_bpermute_b32 v99, v17, v195
	ds_bpermute_b32 v100, v17, v196
	ds_bpermute_b32 v101, v17, v197
	ds_bpermute_b32 v102, v17, v198
	ds_bpermute_b32 v103, v17, v199
	ds_bpermute_b32 v104, v17, v200
	ds_bpermute_b32 v105, v17, v201
	ds_bpermute_b32 v106, v17, v202
	ds_bpermute_b32 v107, v17, v203
	ds_bpermute_b32 v108, v17, v204
	ds_bpermute_b32 v109, v17, v205
	ds_bpermute_b32 v110, v17, v206
	ds_bpermute_b32 v111, v17, v207
	s_waitcnt lgkmcnt(8)
	v_add_f32_e32 v192, v192, v96
	v_add_f32_e32 v193, v193, v97
	v_add_f32_e32 v194, v194, v98
	v_add_f32_e32 v195, v195, v99
	v_add_f32_e32 v196, v196, v100
	v_add_f32_e32 v197, v197, v101
	v_add_f32_e32 v198, v198, v102
	v_add_f32_e32 v199, v199, v103
	s_waitcnt lgkmcnt(0)
	v_add_f32_e32 v200, v200, v104
	v_add_f32_e32 v201, v201, v105
	v_add_f32_e32 v202, v202, v106
	v_add_f32_e32 v203, v203, v107
	v_add_f32_e32 v204, v204, v108
	v_add_f32_e32 v205, v205, v109
	v_add_f32_e32 v206, v206, v110
	v_add_f32_e32 v207, v207, v111
	ds_bpermute_b32 v96, v83, v192
	ds_bpermute_b32 v97, v83, v193
	ds_bpermute_b32 v98, v83, v194
	ds_bpermute_b32 v99, v83, v195
	ds_bpermute_b32 v100, v83, v196
	ds_bpermute_b32 v101, v83, v197
	ds_bpermute_b32 v102, v83, v198
	ds_bpermute_b32 v103, v83, v199
	ds_bpermute_b32 v104, v83, v200
	ds_bpermute_b32 v105, v83, v201
	ds_bpermute_b32 v106, v83, v202
	ds_bpermute_b32 v107, v83, v203
	ds_bpermute_b32 v108, v83, v204
	ds_bpermute_b32 v109, v83, v205
	ds_bpermute_b32 v110, v83, v206
	ds_bpermute_b32 v111, v83, v207
	s_waitcnt lgkmcnt(8)
	v_add_f32_e32 v192, v192, v96
	v_add_f32_e32 v193, v193, v97
	v_add_f32_e32 v194, v194, v98
	v_add_f32_e32 v195, v195, v99
	v_add_f32_e32 v196, v196, v100
	v_add_f32_e32 v197, v197, v101
	v_add_f32_e32 v198, v198, v102
	v_add_f32_e32 v199, v199, v103
	s_waitcnt lgkmcnt(0)
	v_add_f32_e32 v200, v200, v104
	v_add_f32_e32 v201, v201, v105
	v_add_f32_e32 v202, v202, v106
	v_add_f32_e32 v203, v203, v107
	v_add_f32_e32 v204, v204, v108
	v_add_f32_e32 v205, v205, v109
	v_add_f32_e32 v206, v206, v110
	v_add_f32_e32 v207, v207, v111
	ds_bpermute_b32 v96, v82, v192
	ds_bpermute_b32 v97, v82, v193
	ds_bpermute_b32 v98, v82, v194
	ds_bpermute_b32 v99, v82, v195
	ds_bpermute_b32 v100, v82, v196
	ds_bpermute_b32 v101, v82, v197
	ds_bpermute_b32 v102, v82, v198
	ds_bpermute_b32 v103, v82, v199
	ds_bpermute_b32 v104, v82, v200
	ds_bpermute_b32 v105, v82, v201
	ds_bpermute_b32 v106, v82, v202
	ds_bpermute_b32 v107, v82, v203
	ds_bpermute_b32 v108, v82, v204
	ds_bpermute_b32 v109, v82, v205
	ds_bpermute_b32 v110, v82, v206
	ds_bpermute_b32 v111, v82, v207
	s_waitcnt lgkmcnt(8)
	v_add_f32_e32 v192, v192, v96
	v_add_f32_e32 v193, v193, v97
	v_add_f32_e32 v194, v194, v98
	v_add_f32_e32 v195, v195, v99
	v_add_f32_e32 v196, v196, v100
	v_add_f32_e32 v197, v197, v101
	v_add_f32_e32 v198, v198, v102
	v_add_f32_e32 v199, v199, v103
	s_waitcnt lgkmcnt(0)
	v_add_f32_e32 v200, v200, v104
	v_add_f32_e32 v201, v201, v105
	v_add_f32_e32 v202, v202, v106
	v_add_f32_e32 v203, v203, v107
	v_add_f32_e32 v204, v204, v108
	v_add_f32_e32 v205, v205, v109
	v_add_f32_e32 v206, v206, v110
	v_add_f32_e32 v207, v207, v111
	ds_bpermute_b32 v96, v14, v192
	ds_bpermute_b32 v97, v14, v193
	ds_bpermute_b32 v98, v14, v194
	ds_bpermute_b32 v99, v14, v195
	ds_bpermute_b32 v100, v14, v196
	ds_bpermute_b32 v101, v14, v197
	ds_bpermute_b32 v102, v14, v198
	ds_bpermute_b32 v103, v14, v199
	ds_bpermute_b32 v104, v14, v200
	ds_bpermute_b32 v105, v14, v201
	ds_bpermute_b32 v106, v14, v202
	ds_bpermute_b32 v107, v14, v203
	ds_bpermute_b32 v108, v14, v204
	ds_bpermute_b32 v109, v14, v205
	ds_bpermute_b32 v110, v14, v206
	ds_bpermute_b32 v111, v14, v207
	s_waitcnt lgkmcnt(8)
	v_add_f32_e32 v192, v192, v96
	v_add_f32_e32 v193, v193, v97
	v_add_f32_e32 v194, v194, v98
	v_add_f32_e32 v195, v195, v99
	v_add_f32_e32 v196, v196, v100
	v_add_f32_e32 v197, v197, v101
	v_add_f32_e32 v198, v198, v102
	v_add_f32_e32 v199, v199, v103
	s_waitcnt lgkmcnt(0)
; __device__ __forceinline__ void sg_unit(const Params& P, int l, int chunk, char* shm, float* ssb) {
;     ...
;         const float mean = wave_sum((v[0] + v[1]) + (v[2] + v[3])) * (1.f / 256.f);
;         v = v - mean; const f32x4 sq = v * v;
;         const float rstd = 1.f / sqrtf(wave_sum((sq[0] + sq[1]) + (sq[2] + sq[3])) * (1.f / 256.f) + LN_EPS);
	v_add_f32_e32 v200, v200, v104
	v_add_f32_e32 v201, v201, v105
	v_add_f32_e32 v202, v202, v106
	v_add_f32_e32 v203, v203, v107
	v_add_f32_e32 v204, v204, v108
	v_add_f32_e32 v205, v205, v109
	v_add_f32_e32 v206, v206, v110
	v_add_f32_e32 v207, v207, v111
	ds_bpermute_b32 v96, v15, v192
	ds_bpermute_b32 v97, v15, v193
	ds_bpermute_b32 v98, v15, v194
	ds_bpermute_b32 v99, v15, v195
	ds_bpermute_b32 v100, v15, v196
	ds_bpermute_b32 v101, v15, v197
	ds_bpermute_b32 v102, v15, v198
	ds_bpermute_b32 v103, v15, v199
	ds_bpermute_b32 v104, v15, v200
	ds_bpermute_b32 v105, v15, v201
	ds_bpermute_b32 v106, v15, v202
	ds_bpermute_b32 v107, v15, v203
	ds_bpermute_b32 v108, v15, v204
	ds_bpermute_b32 v109, v15, v205
	ds_bpermute_b32 v110, v15, v206
	ds_bpermute_b32 v111, v15, v207
	s_waitcnt lgkmcnt(8)
	v_add_f32_e32 v192, v192, v96
	v_add_f32_e32 v193, v193, v97
	v_add_f32_e32 v194, v194, v98
	v_add_f32_e32 v195, v195, v99
	v_add_f32_e32 v196, v196, v100
	v_add_f32_e32 v197, v197, v101
	v_add_f32_e32 v198, v198, v102
	v_add_f32_e32 v199, v199, v103
	s_waitcnt lgkmcnt(0)
	v_add_f32_e32 v200, v200, v104
	v_add_f32_e32 v201, v201, v105
	v_add_f32_e32 v202, v202, v106
	v_add_f32_e32 v203, v203, v107
	v_add_f32_e32 v204, v204, v108
	v_add_f32_e32 v205, v205, v109
	v_add_f32_e32 v206, v206, v110
	v_add_f32_e32 v207, v207, v111
	ds_bpermute_b32 v96, v18, v192
	ds_bpermute_b32 v97, v18, v193
	ds_bpermute_b32 v98, v18, v194
	ds_bpermute_b32 v99, v18, v195
	ds_bpermute_b32 v100, v18, v196
	ds_bpermute_b32 v101, v18, v197
	ds_bpermute_b32 v102, v18, v198
	ds_bpermute_b32 v103, v18, v199
	ds_bpermute_b32 v104, v18, v200
	ds_bpermute_b32 v105, v18, v201
	ds_bpermute_b32 v106, v18, v202
	ds_bpermute_b32 v107, v18, v203
	ds_bpermute_b32 v108, v18, v204
	ds_bpermute_b32 v109, v18, v205
	ds_bpermute_b32 v110, v18, v206
	ds_bpermute_b32 v111, v18, v207
	s_waitcnt lgkmcnt(8)
	v_add_f32_e32 v192, v192, v96
	v_add_f32_e32 v193, v193, v97
	v_add_f32_e32 v194, v194, v98
	v_add_f32_e32 v195, v195, v99
	v_add_f32_e32 v196, v196, v100
	v_add_f32_e32 v197, v197, v101
	v_add_f32_e32 v198, v198, v102
	v_add_f32_e32 v199, v199, v103
	s_waitcnt lgkmcnt(0)
	v_add_f32_e32 v200, v200, v104
	v_add_f32_e32 v201, v201, v105
	v_add_f32_e32 v202, v202, v106
	v_add_f32_e32 v203, v203, v107
	v_add_f32_e32 v204, v204, v108
	v_add_f32_e32 v205, v205, v109
	v_add_f32_e32 v206, v206, v110
	v_add_f32_e32 v207, v207, v111
	v_fmac_f32_e32 v129, 0xbb800000, v192
	v_fmac_f32_e32 v131, 0xbb800000, v192
	v_fmac_f32_e32 v130, 0xbb800000, v192
	v_fmac_f32_e32 v128, 0xbb800000, v192
	v_fmac_f32_e32 v133, 0xbb800000, v193
	v_fmac_f32_e32 v135, 0xbb800000, v193
	v_fmac_f32_e32 v134, 0xbb800000, v193
	v_fmac_f32_e32 v132, 0xbb800000, v193
	v_fmac_f32_e32 v137, 0xbb800000, v194
	v_fmac_f32_e32 v139, 0xbb800000, v194
	v_fmac_f32_e32 v138, 0xbb800000, v194
	v_fmac_f32_e32 v136, 0xbb800000, v194
	v_fmac_f32_e32 v141, 0xbb800000, v195
	v_fmac_f32_e32 v143, 0xbb800000, v195
	v_fmac_f32_e32 v142, 0xbb800000, v195
	v_fmac_f32_e32 v140, 0xbb800000, v195
	v_fmac_f32_e32 v145, 0xbb800000, v196
	v_fmac_f32_e32 v147, 0xbb800000, v196
	v_fmac_f32_e32 v146, 0xbb800000, v196
	v_fmac_f32_e32 v144, 0xbb800000, v196
	v_fmac_f32_e32 v149, 0xbb800000, v197
	v_fmac_f32_e32 v151, 0xbb800000, v197
	v_fmac_f32_e32 v150, 0xbb800000, v197
	v_fmac_f32_e32 v148, 0xbb800000, v197
	v_fmac_f32_e32 v153, 0xbb800000, v198
	v_fmac_f32_e32 v155, 0xbb800000, v198
	v_fmac_f32_e32 v154, 0xbb800000, v198
	v_fmac_f32_e32 v152, 0xbb800000, v198
	v_fmac_f32_e32 v157, 0xbb800000, v199
	v_fmac_f32_e32 v159, 0xbb800000, v199
	v_fmac_f32_e32 v158, 0xbb800000, v199
	v_fmac_f32_e32 v156, 0xbb800000, v199
	v_fmac_f32_e32 v161, 0xbb800000, v200
	v_fmac_f32_e32 v163, 0xbb800000, v200
	v_fmac_f32_e32 v162, 0xbb800000, v200
	v_fmac_f32_e32 v160, 0xbb800000, v200
	v_fmac_f32_e32 v165, 0xbb800000, v201
	v_fmac_f32_e32 v167, 0xbb800000, v201
	v_fmac_f32_e32 v166, 0xbb800000, v201
	v_fmac_f32_e32 v164, 0xbb800000, v201
	v_fmac_f32_e32 v169, 0xbb800000, v202
	v_fmac_f32_e32 v171, 0xbb800000, v202
	v_fmac_f32_e32 v170, 0xbb800000, v202
	v_fmac_f32_e32 v168, 0xbb800000, v202
	v_fmac_f32_e32 v173, 0xbb800000, v203
	v_fmac_f32_e32 v175, 0xbb800000, v203
	v_fmac_f32_e32 v174, 0xbb800000, v203
	v_fmac_f32_e32 v172, 0xbb800000, v203
	v_fmac_f32_e32 v177, 0xbb800000, v204
	v_fmac_f32_e32 v179, 0xbb800000, v204
	v_fmac_f32_e32 v178, 0xbb800000, v204
	v_fmac_f32_e32 v176, 0xbb800000, v204
	v_fmac_f32_e32 v181, 0xbb800000, v205
	v_fmac_f32_e32 v183, 0xbb800000, v205
	v_fmac_f32_e32 v182, 0xbb800000, v205
	v_fmac_f32_e32 v180, 0xbb800000, v205
	v_fmac_f32_e32 v185, 0xbb800000, v206
	v_fmac_f32_e32 v187, 0xbb800000, v206
	v_fmac_f32_e32 v186, 0xbb800000, v206
	v_fmac_f32_e32 v184, 0xbb800000, v206
	v_fmac_f32_e32 v189, 0xbb800000, v207
	v_fmac_f32_e32 v191, 0xbb800000, v207
	v_fmac_f32_e32 v190, 0xbb800000, v207
	v_fmac_f32_e32 v188, 0xbb800000, v207
	v_mul_f32_e32 v208, v128, v128
	v_mul_f32_e32 v209, v129, v129
	v_mul_f32_e32 v210, v130, v130
	v_mul_f32_e32 v211, v131, v131
	v_add_f32_e32 v208, v209, v208
	v_add_f32_e32 v210, v210, v211
	v_add_f32_e32 v192, v208, v210
	v_mul_f32_e32 v208, v132, v132
	v_mul_f32_e32 v209, v133, v133
	v_mul_f32_e32 v210, v134, v134
	v_mul_f32_e32 v211, v135, v135
	v_add_f32_e32 v208, v209, v208
	v_add_f32_e32 v210, v210, v211
	v_add_f32_e32 v193, v208, v210
	v_mul_f32_e32 v208, v136, v136
	v_mul_f32_e32 v209, v137, v137
	v_mul_f32_e32 v210, v138, v138
	v_mul_f32_e32 v211, v139, v139
	v_add_f32_e32 v208, v209, v208
	v_add_f32_e32 v210, v210, v211
	v_add_f32_e32 v194, v208, v210
	v_mul_f32_e32 v208, v140, v140
	v_mul_f32_e32 v209, v141, v141
; __device__ __forceinline__ void sg_unit(const Params& P, int l, int chunk, char* shm, float* ssb) {
;     ...
;         v = v - mean; const f32x4 sq = v * v;
;         const float rstd = 1.f / sqrtf(wave_sum((sq[0] + sq[1]) + (sq[2] + sq[3])) * (1.f / 256.f) + LN_EPS);
	v_mul_f32_e32 v210, v142, v142
	v_mul_f32_e32 v211, v143, v143
	v_add_f32_e32 v208, v209, v208
	v_add_f32_e32 v210, v210, v211
	v_add_f32_e32 v195, v208, v210
	v_mul_f32_e32 v208, v144, v144
	v_mul_f32_e32 v209, v145, v145
	v_mul_f32_e32 v210, v146, v146
	v_mul_f32_e32 v211, v147, v147
	v_add_f32_e32 v208, v209, v208
	v_add_f32_e32 v210, v210, v211
	v_add_f32_e32 v196, v208, v210
	v_mul_f32_e32 v208, v148, v148
	v_mul_f32_e32 v209, v149, v149
	v_mul_f32_e32 v210, v150, v150
	v_mul_f32_e32 v211, v151, v151
	v_add_f32_e32 v208, v209, v208
	v_add_f32_e32 v210, v210, v211
	v_add_f32_e32 v197, v208, v210
	v_mul_f32_e32 v208, v152, v152
	v_mul_f32_e32 v209, v153, v153
	v_mul_f32_e32 v210, v154, v154
	v_mul_f32_e32 v211, v155, v155
	v_add_f32_e32 v208, v209, v208
	v_add_f32_e32 v210, v210, v211
	v_add_f32_e32 v198, v208, v210
	v_mul_f32_e32 v208, v156, v156
	v_mul_f32_e32 v209, v157, v157
	v_mul_f32_e32 v210, v158, v158
	v_mul_f32_e32 v211, v159, v159
	v_add_f32_e32 v208, v209, v208
	v_add_f32_e32 v210, v210, v211
	v_add_f32_e32 v199, v208, v210
	v_mul_f32_e32 v208, v160, v160
	v_mul_f32_e32 v209, v161, v161
	v_mul_f32_e32 v210, v162, v162
	v_mul_f32_e32 v211, v163, v163
	v_add_f32_e32 v208, v209, v208
	v_add_f32_e32 v210, v210, v211
	v_add_f32_e32 v200, v208, v210
	v_mul_f32_e32 v208, v164, v164
	v_mul_f32_e32 v209, v165, v165
	v_mul_f32_e32 v210, v166, v166
	v_mul_f32_e32 v211, v167, v167
	v_add_f32_e32 v208, v209, v208
	v_add_f32_e32 v210, v210, v211
	v_add_f32_e32 v201, v208, v210
	v_mul_f32_e32 v208, v168, v168
	v_mul_f32_e32 v209, v169, v169
	v_mul_f32_e32 v210, v170, v170
	v_mul_f32_e32 v211, v171, v171
	v_add_f32_e32 v208, v209, v208
	v_add_f32_e32 v210, v210, v211
	v_add_f32_e32 v202, v208, v210
	v_mul_f32_e32 v208, v172, v172
	v_mul_f32_e32 v209, v173, v173
	v_mul_f32_e32 v210, v174, v174
	v_mul_f32_e32 v211, v175, v175
	v_add_f32_e32 v208, v209, v208
	v_add_f32_e32 v210, v210, v211
	v_add_f32_e32 v203, v208, v210
	v_mul_f32_e32 v208, v176, v176
	v_mul_f32_e32 v209, v177, v177
	v_mul_f32_e32 v210, v178, v178
	v_mul_f32_e32 v211, v179, v179
	v_add_f32_e32 v208, v209, v208
	v_add_f32_e32 v210, v210, v211
	v_add_f32_e32 v204, v208, v210
	v_mul_f32_e32 v208, v180, v180
	v_mul_f32_e32 v209, v181, v181
	v_mul_f32_e32 v210, v182, v182
	v_mul_f32_e32 v211, v183, v183
	v_add_f32_e32 v208, v209, v208
	v_add_f32_e32 v210, v210, v211
	v_add_f32_e32 v205, v208, v210
	v_mul_f32_e32 v208, v184, v184
	v_mul_f32_e32 v209, v185, v185
	v_mul_f32_e32 v210, v186, v186
	v_mul_f32_e32 v211, v187, v187
	v_add_f32_e32 v208, v209, v208
	v_add_f32_e32 v210, v210, v211
	v_add_f32_e32 v206, v208, v210
	v_mul_f32_e32 v208, v188, v188
	v_mul_f32_e32 v209, v189, v189
	v_mul_f32_e32 v210, v190, v190
	v_mul_f32_e32 v211, v191, v191
	v_add_f32_e32 v208, v209, v208
	v_add_f32_e32 v210, v210, v211
	v_add_f32_e32 v207, v208, v210
	ds_bpermute_b32 v96, v17, v192
	ds_bpermute_b32 v97, v17, v193
	ds_bpermute_b32 v98, v17, v194
	ds_bpermute_b32 v99, v17, v195
	ds_bpermute_b32 v100, v17, v196
	ds_bpermute_b32 v101, v17, v197
	ds_bpermute_b32 v102, v17, v198
	ds_bpermute_b32 v103, v17, v199
	ds_bpermute_b32 v104, v17, v200
	ds_bpermute_b32 v105, v17, v201
	ds_bpermute_b32 v106, v17, v202
	ds_bpermute_b32 v107, v17, v203
	ds_bpermute_b32 v108, v17, v204
	ds_bpermute_b32 v109, v17, v205
	ds_bpermute_b32 v110, v17, v206
	ds_bpermute_b32 v111, v17, v207
	s_waitcnt lgkmcnt(8)
	v_add_f32_e32 v192, v192, v96
	v_add_f32_e32 v193, v193, v97
	v_add_f32_e32 v194, v194, v98
	v_add_f32_e32 v195, v195, v99
	v_add_f32_e32 v196, v196, v100
	v_add_f32_e32 v197, v197, v101
	v_add_f32_e32 v198, v198, v102
	v_add_f32_e32 v199, v199, v103
	s_waitcnt lgkmcnt(0)
	v_add_f32_e32 v200, v200, v104
	v_add_f32_e32 v201, v201, v105
	v_add_f32_e32 v202, v202, v106
	v_add_f32_e32 v203, v203, v107
	v_add_f32_e32 v204, v204, v108
	v_add_f32_e32 v205, v205, v109
	v_add_f32_e32 v206, v206, v110
	v_add_f32_e32 v207, v207, v111
	ds_bpermute_b32 v96, v83, v192
	ds_bpermute_b32 v97, v83, v193
	ds_bpermute_b32 v98, v83, v194
	ds_bpermute_b32 v99, v83, v195
	ds_bpermute_b32 v100, v83, v196
	ds_bpermute_b32 v101, v83, v197
	ds_bpermute_b32 v102, v83, v198
	ds_bpermute_b32 v103, v83, v199
	ds_bpermute_b32 v104, v83, v200
	ds_bpermute_b32 v105, v83, v201
	ds_bpermute_b32 v106, v83, v202
	ds_bpermute_b32 v107, v83, v203
	ds_bpermute_b32 v108, v83, v204
	ds_bpermute_b32 v109, v83, v205
	ds_bpermute_b32 v110, v83, v206
	ds_bpermute_b32 v111, v83, v207
	s_waitcnt lgkmcnt(8)
	v_add_f32_e32 v192, v192, v96
	v_add_f32_e32 v193, v193, v97
	v_add_f32_e32 v194, v194, v98
	v_add_f32_e32 v195, v195, v99
	v_add_f32_e32 v196, v196, v100
	v_add_f32_e32 v197, v197, v101
	v_add_f32_e32 v198, v198, v102
	v_add_f32_e32 v199, v199, v103
	s_waitcnt lgkmcnt(0)
	v_add_f32_e32 v200, v200, v104
	v_add_f32_e32 v201, v201, v105
	v_add_f32_e32 v202, v202, v106
	v_add_f32_e32 v203, v203, v107
	v_add_f32_e32 v204, v204, v108
	v_add_f32_e32 v205, v205, v109
	v_add_f32_e32 v206, v206, v110
	v_add_f32_e32 v207, v207, v111
	ds_bpermute_b32 v96, v82, v192
	ds_bpermute_b32 v97, v82, v193
	ds_bpermute_b32 v98, v82, v194
	ds_bpermute_b32 v99, v82, v195
	ds_bpermute_b32 v100, v82, v196
	ds_bpermute_b32 v101, v82, v197
	ds_bpermute_b32 v102, v82, v198
	ds_bpermute_b32 v103, v82, v199
	ds_bpermute_b32 v104, v82, v200
	ds_bpermute_b32 v105, v82, v201
	ds_bpermute_b32 v106, v82, v202
	ds_bpermute_b32 v107, v82, v203
	ds_bpermute_b32 v108, v82, v204
	ds_bpermute_b32 v109, v82, v205
	ds_bpermute_b32 v110, v82, v206
	ds_bpermute_b32 v111, v82, v207
	s_waitcnt lgkmcnt(8)
; __device__ __forceinline__ unsigned cvtpk_s(float lo, float hi) { typedef __bf16 bf16x2_t __attribute__((ext_vector_type(2))); f32x2 v = {lo, hi}; bf16x2_t b = __builtin_convertvector(v, bf16x2_t); return __builtin_bit_cast(unsigned, b); }
; __device__ __forceinline__ void sg_unit(const Params& P, int l, int chunk, char* shm, float* ssb) {
;     ...
;         const float rstd = 1.f / sqrtf(wave_sum((sq[0] + sq[1]) + (sq[2] + sq[3])) * (1.f / 256.f) + LN_EPS);
;         v = v * rstd * g4;
; #pragma unroll
;         for (int j = 0; j < 4; ++j) vt[(4 * lane + j) * SG_VT_PITCH + q] = (bf16_t)(at::cvtpk_s(v[j], 0.f) & 0xffffu);
	v_add_f32_e32 v192, v192, v96
	v_add_f32_e32 v193, v193, v97
	v_add_f32_e32 v194, v194, v98
	v_add_f32_e32 v195, v195, v99
	v_add_f32_e32 v196, v196, v100
	v_add_f32_e32 v197, v197, v101
	v_add_f32_e32 v198, v198, v102
	v_add_f32_e32 v199, v199, v103
	s_waitcnt lgkmcnt(0)
	v_add_f32_e32 v200, v200, v104
	v_add_f32_e32 v201, v201, v105
	v_add_f32_e32 v202, v202, v106
	v_add_f32_e32 v203, v203, v107
	v_add_f32_e32 v204, v204, v108
	v_add_f32_e32 v205, v205, v109
	v_add_f32_e32 v206, v206, v110
	v_add_f32_e32 v207, v207, v111
	ds_bpermute_b32 v96, v14, v192
	ds_bpermute_b32 v97, v14, v193
	ds_bpermute_b32 v98, v14, v194
	ds_bpermute_b32 v99, v14, v195
	ds_bpermute_b32 v100, v14, v196
	ds_bpermute_b32 v101, v14, v197
	ds_bpermute_b32 v102, v14, v198
	ds_bpermute_b32 v103, v14, v199
	ds_bpermute_b32 v104, v14, v200
	ds_bpermute_b32 v105, v14, v201
	ds_bpermute_b32 v106, v14, v202
	ds_bpermute_b32 v107, v14, v203
	ds_bpermute_b32 v108, v14, v204
	ds_bpermute_b32 v109, v14, v205
	ds_bpermute_b32 v110, v14, v206
	ds_bpermute_b32 v111, v14, v207
	s_waitcnt lgkmcnt(8)
	v_add_f32_e32 v192, v192, v96
	v_add_f32_e32 v193, v193, v97
	v_add_f32_e32 v194, v194, v98
	v_add_f32_e32 v195, v195, v99
	v_add_f32_e32 v196, v196, v100
	v_add_f32_e32 v197, v197, v101
	v_add_f32_e32 v198, v198, v102
	v_add_f32_e32 v199, v199, v103
	s_waitcnt lgkmcnt(0)
	v_add_f32_e32 v200, v200, v104
	v_add_f32_e32 v201, v201, v105
	v_add_f32_e32 v202, v202, v106
	v_add_f32_e32 v203, v203, v107
	v_add_f32_e32 v204, v204, v108
	v_add_f32_e32 v205, v205, v109
	v_add_f32_e32 v206, v206, v110
	v_add_f32_e32 v207, v207, v111
	ds_bpermute_b32 v96, v15, v192
	ds_bpermute_b32 v97, v15, v193
	ds_bpermute_b32 v98, v15, v194
	ds_bpermute_b32 v99, v15, v195
	ds_bpermute_b32 v100, v15, v196
	ds_bpermute_b32 v101, v15, v197
	ds_bpermute_b32 v102, v15, v198
	ds_bpermute_b32 v103, v15, v199
	ds_bpermute_b32 v104, v15, v200
	ds_bpermute_b32 v105, v15, v201
	ds_bpermute_b32 v106, v15, v202
	ds_bpermute_b32 v107, v15, v203
	ds_bpermute_b32 v108, v15, v204
	ds_bpermute_b32 v109, v15, v205
	ds_bpermute_b32 v110, v15, v206
	ds_bpermute_b32 v111, v15, v207
	s_waitcnt lgkmcnt(8)
	v_add_f32_e32 v192, v192, v96
	v_add_f32_e32 v193, v193, v97
	v_add_f32_e32 v194, v194, v98
	v_add_f32_e32 v195, v195, v99
	v_add_f32_e32 v196, v196, v100
	v_add_f32_e32 v197, v197, v101
	v_add_f32_e32 v198, v198, v102
	v_add_f32_e32 v199, v199, v103
	s_waitcnt lgkmcnt(0)
	v_add_f32_e32 v200, v200, v104
	v_add_f32_e32 v201, v201, v105
	v_add_f32_e32 v202, v202, v106
	v_add_f32_e32 v203, v203, v107
	v_add_f32_e32 v204, v204, v108
	v_add_f32_e32 v205, v205, v109
	v_add_f32_e32 v206, v206, v110
	v_add_f32_e32 v207, v207, v111
	ds_bpermute_b32 v96, v18, v192
	ds_bpermute_b32 v97, v18, v193
	ds_bpermute_b32 v98, v18, v194
	ds_bpermute_b32 v99, v18, v195
	ds_bpermute_b32 v100, v18, v196
	ds_bpermute_b32 v101, v18, v197
	ds_bpermute_b32 v102, v18, v198
	ds_bpermute_b32 v103, v18, v199
	ds_bpermute_b32 v104, v18, v200
	ds_bpermute_b32 v105, v18, v201
	ds_bpermute_b32 v106, v18, v202
	ds_bpermute_b32 v107, v18, v203
	ds_bpermute_b32 v108, v18, v204
	ds_bpermute_b32 v109, v18, v205
	ds_bpermute_b32 v110, v18, v206
	ds_bpermute_b32 v111, v18, v207
	s_waitcnt lgkmcnt(8)
	v_add_f32_e32 v192, v192, v96
	v_add_f32_e32 v193, v193, v97
	v_add_f32_e32 v194, v194, v98
	v_add_f32_e32 v195, v195, v99
	v_add_f32_e32 v196, v196, v100
	v_add_f32_e32 v197, v197, v101
	v_add_f32_e32 v198, v198, v102
	v_add_f32_e32 v199, v199, v103
	s_waitcnt lgkmcnt(0)
	v_add_f32_e32 v200, v200, v104
	v_add_f32_e32 v201, v201, v105
	v_add_f32_e32 v202, v202, v106
	v_add_f32_e32 v203, v203, v107
	v_add_f32_e32 v204, v204, v108
	v_add_f32_e32 v205, v205, v109
	v_add_f32_e32 v206, v206, v110
	v_add_f32_e32 v207, v207, v111
	v_fmamk_f32 v192, v192, 0x3b800000, v216
	v_cmp_gt_f32_e32 vcc, s69, v192
	v_mul_f32_e32 v96, 0x4f800000, v192
	s_nop 0
	v_cndmask_b32_e32 v192, v192, v96, vcc
	v_sqrt_f32_e32 v96, v192
	s_nop 0
	v_add_u32_e32 v97, -1, v96
	v_fma_f32 v98, -v97, v96, v192
	v_cmp_ge_f32_e64 s[0:1], 0, v98
	v_add_u32_e32 v98, 1, v96
	s_nop 0
	v_cndmask_b32_e64 v97, v96, v97, s[0:1]
	v_fma_f32 v96, -v98, v96, v192
	v_cmp_lt_f32_e64 s[0:1], 0, v96
	s_nop 1
	v_cndmask_b32_e64 v96, v97, v98, s[0:1]
	v_mul_f32_e32 v97, 0x37800000, v96
	v_cndmask_b32_e32 v96, v96, v97, vcc
	v_cmp_class_f32_e32 vcc, v192, v217
	s_nop 1
	v_cndmask_b32_e32 v192, v96, v192, vcc
	v_div_scale_f32 v96, s[0:1], v192, v192, 1.0
	v_rcp_f32_e32 v97, v96
	s_nop 0
	v_fma_f32 v98, -v96, v97, 1.0
	v_fmac_f32_e32 v97, v98, v97
	v_div_scale_f32 v98, vcc, 1.0, v192, 1.0
	v_mul_f32_e32 v99, v98, v97
	v_fma_f32 v100, -v96, v99, v98
	v_fmac_f32_e32 v99, v100, v97
	v_fma_f32 v96, -v96, v99, v98
	v_div_fmas_f32 v96, v96, v97, v99
	v_div_fixup_f32 v192, v96, v192, 1.0
	v_mul_f32_e32 v128, v128, v192
	v_mul_f32_e32 v129, v129, v192
	v_mul_f32_e32 v130, v130, v192
	v_mul_f32_e32 v131, v131, v192
	v_mul_f32_e32 v96, v2, v128
	v_cvt_pk_bf16_f32 v96, v96, s0
	v_mul_f32_e32 v97, v3, v129
	v_cvt_pk_bf16_f32 v97, v97, s0
	v_mul_f32_e32 v98, v4, v130
	v_cvt_pk_bf16_f32 v98, v98, s0
	v_mul_f32_e32 v99, v5, v131
	v_cvt_pk_bf16_f32 v99, v99, s0
	ds_write_b16 v19, v96 offset:0
	ds_write_b16 v19, v97 offset:272
	ds_write_b16 v19, v98 offset:544
	ds_write_b16 v19, v99 offset:816
	v_fmamk_f32 v193, v193, 0x3b800000, v216
	v_cmp_gt_f32_e32 vcc, s69, v193
	v_mul_f32_e32 v96, 0x4f800000, v193
	s_nop 0
	v_cndmask_b32_e32 v193, v193, v96, vcc
	v_sqrt_f32_e32 v96, v193
	s_nop 0
	v_add_u32_e32 v97, -1, v96
	v_fma_f32 v98, -v97, v96, v193
	v_cmp_ge_f32_e64 s[0:1], 0, v98
	v_add_u32_e32 v98, 1, v96
	s_nop 0
	v_cndmask_b32_e64 v97, v96, v97, s[0:1]
; __device__ __forceinline__ unsigned cvtpk_s(float lo, float hi) { typedef __bf16 bf16x2_t __attribute__((ext_vector_type(2))); f32x2 v = {lo, hi}; bf16x2_t b = __builtin_convertvector(v, bf16x2_t); return __builtin_bit_cast(unsigned, b); }
; __device__ __forceinline__ void sg_unit(const Params& P, int l, int chunk, char* shm, float* ssb) {
;     ...
;         const float rstd = 1.f / sqrtf(wave_sum((sq[0] + sq[1]) + (sq[2] + sq[3])) * (1.f / 256.f) + LN_EPS);
;         v = v * rstd * g4;
; #pragma unroll
;         for (int j = 0; j < 4; ++j) vt[(4 * lane + j) * SG_VT_PITCH + q] = (bf16_t)(at::cvtpk_s(v[j], 0.f) & 0xffffu);
	v_fma_f32 v96, -v98, v96, v193
	v_cmp_lt_f32_e64 s[0:1], 0, v96
	s_nop 1
	v_cndmask_b32_e64 v96, v97, v98, s[0:1]
	v_mul_f32_e32 v97, 0x37800000, v96
	v_cndmask_b32_e32 v96, v96, v97, vcc
	v_cmp_class_f32_e32 vcc, v193, v217
	s_nop 1
	v_cndmask_b32_e32 v193, v96, v193, vcc
	v_div_scale_f32 v96, s[0:1], v193, v193, 1.0
	v_rcp_f32_e32 v97, v96
	s_nop 0
	v_fma_f32 v98, -v96, v97, 1.0
	v_fmac_f32_e32 v97, v98, v97
	v_div_scale_f32 v98, vcc, 1.0, v193, 1.0
	v_mul_f32_e32 v99, v98, v97
	v_fma_f32 v100, -v96, v99, v98
	v_fmac_f32_e32 v99, v100, v97
	v_fma_f32 v96, -v96, v99, v98
	v_div_fmas_f32 v96, v96, v97, v99
	v_div_fixup_f32 v193, v96, v193, 1.0
	v_mul_f32_e32 v132, v132, v193
	v_mul_f32_e32 v133, v133, v193
	v_mul_f32_e32 v134, v134, v193
	v_mul_f32_e32 v135, v135, v193
	v_mul_f32_e32 v96, v2, v132
	v_cvt_pk_bf16_f32 v96, v96, s0
	v_mul_f32_e32 v97, v3, v133
	v_cvt_pk_bf16_f32 v97, v97, s0
	v_mul_f32_e32 v98, v4, v134
	v_cvt_pk_bf16_f32 v98, v98, s0
	v_mul_f32_e32 v99, v5, v135
	v_cvt_pk_bf16_f32 v99, v99, s0
	ds_write_b16 v19, v96 offset:2
	ds_write_b16 v19, v97 offset:274
	ds_write_b16 v19, v98 offset:546
	ds_write_b16 v19, v99 offset:818
	v_fmamk_f32 v194, v194, 0x3b800000, v216
	v_cmp_gt_f32_e32 vcc, s69, v194
	v_mul_f32_e32 v96, 0x4f800000, v194
	s_nop 0
	v_cndmask_b32_e32 v194, v194, v96, vcc
	v_sqrt_f32_e32 v96, v194
	s_nop 0
	v_add_u32_e32 v97, -1, v96
	v_fma_f32 v98, -v97, v96, v194
	v_cmp_ge_f32_e64 s[0:1], 0, v98
	v_add_u32_e32 v98, 1, v96
	s_nop 0
	v_cndmask_b32_e64 v97, v96, v97, s[0:1]
	v_fma_f32 v96, -v98, v96, v194
	v_cmp_lt_f32_e64 s[0:1], 0, v96
	s_nop 1
	v_cndmask_b32_e64 v96, v97, v98, s[0:1]
	v_mul_f32_e32 v97, 0x37800000, v96
	v_cndmask_b32_e32 v96, v96, v97, vcc
	v_cmp_class_f32_e32 vcc, v194, v217
	s_nop 1
	v_cndmask_b32_e32 v194, v96, v194, vcc
	v_div_scale_f32 v96, s[0:1], v194, v194, 1.0
	v_rcp_f32_e32 v97, v96
	s_nop 0
	v_fma_f32 v98, -v96, v97, 1.0
	v_fmac_f32_e32 v97, v98, v97
	v_div_scale_f32 v98, vcc, 1.0, v194, 1.0
	v_mul_f32_e32 v99, v98, v97
	v_fma_f32 v100, -v96, v99, v98
	v_fmac_f32_e32 v99, v100, v97
	v_fma_f32 v96, -v96, v99, v98
	v_div_fmas_f32 v96, v96, v97, v99
	v_div_fixup_f32 v194, v96, v194, 1.0
	v_mul_f32_e32 v136, v136, v194
	v_mul_f32_e32 v137, v137, v194
	v_mul_f32_e32 v138, v138, v194
	v_mul_f32_e32 v139, v139, v194
	v_mul_f32_e32 v96, v2, v136
	v_cvt_pk_bf16_f32 v96, v96, s0
	v_mul_f32_e32 v97, v3, v137
	v_cvt_pk_bf16_f32 v97, v97, s0
	v_mul_f32_e32 v98, v4, v138
	v_cvt_pk_bf16_f32 v98, v98, s0
	v_mul_f32_e32 v99, v5, v139
	v_cvt_pk_bf16_f32 v99, v99, s0
	ds_write_b16 v19, v96 offset:4
	ds_write_b16 v19, v97 offset:276
	ds_write_b16 v19, v98 offset:548
	ds_write_b16 v19, v99 offset:820
	v_fmamk_f32 v195, v195, 0x3b800000, v216
	v_cmp_gt_f32_e32 vcc, s69, v195
	v_mul_f32_e32 v96, 0x4f800000, v195
	s_nop 0
	v_cndmask_b32_e32 v195, v195, v96, vcc
	v_sqrt_f32_e32 v96, v195
	s_nop 0
	v_add_u32_e32 v97, -1, v96
	v_fma_f32 v98, -v97, v96, v195
	v_cmp_ge_f32_e64 s[0:1], 0, v98
	v_add_u32_e32 v98, 1, v96
	s_nop 0
	v_cndmask_b32_e64 v97, v96, v97, s[0:1]
	v_fma_f32 v96, -v98, v96, v195
	v_cmp_lt_f32_e64 s[0:1], 0, v96
	s_nop 1
	v_cndmask_b32_e64 v96, v97, v98, s[0:1]
	v_mul_f32_e32 v97, 0x37800000, v96
	v_cndmask_b32_e32 v96, v96, v97, vcc
	v_cmp_class_f32_e32 vcc, v195, v217
	s_nop 1
	v_cndmask_b32_e32 v195, v96, v195, vcc
	v_div_scale_f32 v96, s[0:1], v195, v195, 1.0
	v_rcp_f32_e32 v97, v96
	s_nop 0
	v_fma_f32 v98, -v96, v97, 1.0
	v_fmac_f32_e32 v97, v98, v97
	v_div_scale_f32 v98, vcc, 1.0, v195, 1.0
	v_mul_f32_e32 v99, v98, v97
	v_fma_f32 v100, -v96, v99, v98
	v_fmac_f32_e32 v99, v100, v97
	v_fma_f32 v96, -v96, v99, v98
	v_div_fmas_f32 v96, v96, v97, v99
	v_div_fixup_f32 v195, v96, v195, 1.0
	v_mul_f32_e32 v140, v140, v195
	v_mul_f32_e32 v141, v141, v195
	v_mul_f32_e32 v142, v142, v195
	v_mul_f32_e32 v143, v143, v195
	v_mul_f32_e32 v96, v2, v140
	v_cvt_pk_bf16_f32 v96, v96, s0
	v_mul_f32_e32 v97, v3, v141
	v_cvt_pk_bf16_f32 v97, v97, s0
	v_mul_f32_e32 v98, v4, v142
	v_cvt_pk_bf16_f32 v98, v98, s0
	v_mul_f32_e32 v99, v5, v143
	v_cvt_pk_bf16_f32 v99, v99, s0
	ds_write_b16 v19, v96 offset:6
	ds_write_b16 v19, v97 offset:278
	ds_write_b16 v19, v98 offset:550
	ds_write_b16 v19, v99 offset:822
	v_fmamk_f32 v196, v196, 0x3b800000, v216
	v_cmp_gt_f32_e32 vcc, s69, v196
	v_mul_f32_e32 v96, 0x4f800000, v196
	s_nop 0
	v_cndmask_b32_e32 v196, v196, v96, vcc
	v_sqrt_f32_e32 v96, v196
	s_nop 0
	v_add_u32_e32 v97, -1, v96
	v_fma_f32 v98, -v97, v96, v196
	v_cmp_ge_f32_e64 s[0:1], 0, v98
	v_add_u32_e32 v98, 1, v96
	s_nop 0
	v_cndmask_b32_e64 v97, v96, v97, s[0:1]
	v_fma_f32 v96, -v98, v96, v196
	v_cmp_lt_f32_e64 s[0:1], 0, v96
	s_nop 1
	v_cndmask_b32_e64 v96, v97, v98, s[0:1]
	v_mul_f32_e32 v97, 0x37800000, v96
	v_cndmask_b32_e32 v96, v96, v97, vcc
	v_cmp_class_f32_e32 vcc, v196, v217
	s_nop 1
	v_cndmask_b32_e32 v196, v96, v196, vcc
	v_div_scale_f32 v96, s[0:1], v196, v196, 1.0
	v_rcp_f32_e32 v97, v96
	s_nop 0
	v_fma_f32 v98, -v96, v97, 1.0
	v_fmac_f32_e32 v97, v98, v97
	v_div_scale_f32 v98, vcc, 1.0, v196, 1.0
	v_mul_f32_e32 v99, v98, v97
	v_fma_f32 v100, -v96, v99, v98
	v_fmac_f32_e32 v99, v100, v97
	v_fma_f32 v96, -v96, v99, v98
	v_div_fmas_f32 v96, v96, v97, v99
	v_div_fixup_f32 v196, v96, v196, 1.0
	v_mul_f32_e32 v144, v144, v196
	v_mul_f32_e32 v145, v145, v196
	v_mul_f32_e32 v146, v146, v196
	v_mul_f32_e32 v147, v147, v196
	v_mul_f32_e32 v96, v2, v144
	v_cvt_pk_bf16_f32 v96, v96, s0
	v_mul_f32_e32 v97, v3, v145
	v_cvt_pk_bf16_f32 v97, v97, s0
	v_mul_f32_e32 v98, v4, v146
	v_cvt_pk_bf16_f32 v98, v98, s0
	v_mul_f32_e32 v99, v5, v147
	v_cvt_pk_bf16_f32 v99, v99, s0
	ds_write_b16 v19, v96 offset:8
; __device__ __forceinline__ unsigned cvtpk_s(float lo, float hi) { typedef __bf16 bf16x2_t __attribute__((ext_vector_type(2))); f32x2 v = {lo, hi}; bf16x2_t b = __builtin_convertvector(v, bf16x2_t); return __builtin_bit_cast(unsigned, b); }
; __device__ __forceinline__ void sg_unit(const Params& P, int l, int chunk, char* shm, float* ssb) {
;     ...
;         const float rstd = 1.f / sqrtf(wave_sum((sq[0] + sq[1]) + (sq[2] + sq[3])) * (1.f / 256.f) + LN_EPS);
;         v = v * rstd * g4;
; #pragma unroll
;         for (int j = 0; j < 4; ++j) vt[(4 * lane + j) * SG_VT_PITCH + q] = (bf16_t)(at::cvtpk_s(v[j], 0.f) & 0xffffu);
	ds_write_b16 v19, v97 offset:280
	ds_write_b16 v19, v98 offset:552
	ds_write_b16 v19, v99 offset:824
	v_fmamk_f32 v197, v197, 0x3b800000, v216
	v_cmp_gt_f32_e32 vcc, s69, v197
	v_mul_f32_e32 v96, 0x4f800000, v197
	s_nop 0
	v_cndmask_b32_e32 v197, v197, v96, vcc
	v_sqrt_f32_e32 v96, v197
	s_nop 0
	v_add_u32_e32 v97, -1, v96
	v_fma_f32 v98, -v97, v96, v197
	v_cmp_ge_f32_e64 s[0:1], 0, v98
	v_add_u32_e32 v98, 1, v96
	s_nop 0
	v_cndmask_b32_e64 v97, v96, v97, s[0:1]
	v_fma_f32 v96, -v98, v96, v197
	v_cmp_lt_f32_e64 s[0:1], 0, v96
	s_nop 1
	v_cndmask_b32_e64 v96, v97, v98, s[0:1]
	v_mul_f32_e32 v97, 0x37800000, v96
	v_cndmask_b32_e32 v96, v96, v97, vcc
	v_cmp_class_f32_e32 vcc, v197, v217
	s_nop 1
	v_cndmask_b32_e32 v197, v96, v197, vcc
	v_div_scale_f32 v96, s[0:1], v197, v197, 1.0
	v_rcp_f32_e32 v97, v96
	s_nop 0
	v_fma_f32 v98, -v96, v97, 1.0
	v_fmac_f32_e32 v97, v98, v97
	v_div_scale_f32 v98, vcc, 1.0, v197, 1.0
	v_mul_f32_e32 v99, v98, v97
	v_fma_f32 v100, -v96, v99, v98
	v_fmac_f32_e32 v99, v100, v97
	v_fma_f32 v96, -v96, v99, v98
	v_div_fmas_f32 v96, v96, v97, v99
	v_div_fixup_f32 v197, v96, v197, 1.0
	v_mul_f32_e32 v148, v148, v197
	v_mul_f32_e32 v149, v149, v197
	v_mul_f32_e32 v150, v150, v197
	v_mul_f32_e32 v151, v151, v197
	v_mul_f32_e32 v96, v2, v148
	v_cvt_pk_bf16_f32 v96, v96, s0
	v_mul_f32_e32 v97, v3, v149
	v_cvt_pk_bf16_f32 v97, v97, s0
	v_mul_f32_e32 v98, v4, v150
	v_cvt_pk_bf16_f32 v98, v98, s0
	v_mul_f32_e32 v99, v5, v151
	v_cvt_pk_bf16_f32 v99, v99, s0
	ds_write_b16 v19, v96 offset:10
	ds_write_b16 v19, v97 offset:282
	ds_write_b16 v19, v98 offset:554
	ds_write_b16 v19, v99 offset:826
	v_fmamk_f32 v198, v198, 0x3b800000, v216
	v_cmp_gt_f32_e32 vcc, s69, v198
	v_mul_f32_e32 v96, 0x4f800000, v198
	s_nop 0
	v_cndmask_b32_e32 v198, v198, v96, vcc
	v_sqrt_f32_e32 v96, v198
	s_nop 0
	v_add_u32_e32 v97, -1, v96
	v_fma_f32 v98, -v97, v96, v198
	v_cmp_ge_f32_e64 s[0:1], 0, v98
	v_add_u32_e32 v98, 1, v96
	s_nop 0
	v_cndmask_b32_e64 v97, v96, v97, s[0:1]
	v_fma_f32 v96, -v98, v96, v198
	v_cmp_lt_f32_e64 s[0:1], 0, v96
	s_nop 1
	v_cndmask_b32_e64 v96, v97, v98, s[0:1]
	v_mul_f32_e32 v97, 0x37800000, v96
	v_cndmask_b32_e32 v96, v96, v97, vcc
	v_cmp_class_f32_e32 vcc, v198, v217
	s_nop 1
	v_cndmask_b32_e32 v198, v96, v198, vcc
	v_div_scale_f32 v96, s[0:1], v198, v198, 1.0
	v_rcp_f32_e32 v97, v96
	s_nop 0
	v_fma_f32 v98, -v96, v97, 1.0
	v_fmac_f32_e32 v97, v98, v97
	v_div_scale_f32 v98, vcc, 1.0, v198, 1.0
	v_mul_f32_e32 v99, v98, v97
	v_fma_f32 v100, -v96, v99, v98
	v_fmac_f32_e32 v99, v100, v97
	v_fma_f32 v96, -v96, v99, v98
	v_div_fmas_f32 v96, v96, v97, v99
	v_div_fixup_f32 v198, v96, v198, 1.0
	v_mul_f32_e32 v152, v152, v198
	v_mul_f32_e32 v153, v153, v198
	v_mul_f32_e32 v154, v154, v198
	v_mul_f32_e32 v155, v155, v198
	v_mul_f32_e32 v96, v2, v152
	v_cvt_pk_bf16_f32 v96, v96, s0
	v_mul_f32_e32 v97, v3, v153
	v_cvt_pk_bf16_f32 v97, v97, s0
	v_mul_f32_e32 v98, v4, v154
	v_cvt_pk_bf16_f32 v98, v98, s0
	v_mul_f32_e32 v99, v5, v155
	v_cvt_pk_bf16_f32 v99, v99, s0
	ds_write_b16 v19, v96 offset:12
	ds_write_b16 v19, v97 offset:284
	ds_write_b16 v19, v98 offset:556
	ds_write_b16 v19, v99 offset:828
	v_fmamk_f32 v199, v199, 0x3b800000, v216
	v_cmp_gt_f32_e32 vcc, s69, v199
	v_mul_f32_e32 v96, 0x4f800000, v199
	s_nop 0
	v_cndmask_b32_e32 v199, v199, v96, vcc
	v_sqrt_f32_e32 v96, v199
	s_nop 0
	v_add_u32_e32 v97, -1, v96
	v_fma_f32 v98, -v97, v96, v199
	v_cmp_ge_f32_e64 s[0:1], 0, v98
	v_add_u32_e32 v98, 1, v96
	s_nop 0
	v_cndmask_b32_e64 v97, v96, v97, s[0:1]
	v_fma_f32 v96, -v98, v96, v199
	v_cmp_lt_f32_e64 s[0:1], 0, v96
	s_nop 1
	v_cndmask_b32_e64 v96, v97, v98, s[0:1]
	v_mul_f32_e32 v97, 0x37800000, v96
	v_cndmask_b32_e32 v96, v96, v97, vcc
	v_cmp_class_f32_e32 vcc, v199, v217
	s_nop 1
	v_cndmask_b32_e32 v199, v96, v199, vcc
	v_div_scale_f32 v96, s[0:1], v199, v199, 1.0
	v_rcp_f32_e32 v97, v96
	s_nop 0
	v_fma_f32 v98, -v96, v97, 1.0
	v_fmac_f32_e32 v97, v98, v97
	v_div_scale_f32 v98, vcc, 1.0, v199, 1.0
	v_mul_f32_e32 v99, v98, v97
	v_fma_f32 v100, -v96, v99, v98
	v_fmac_f32_e32 v99, v100, v97
	v_fma_f32 v96, -v96, v99, v98
	v_div_fmas_f32 v96, v96, v97, v99
	v_div_fixup_f32 v199, v96, v199, 1.0
	v_mul_f32_e32 v156, v156, v199
	v_mul_f32_e32 v157, v157, v199
	v_mul_f32_e32 v158, v158, v199
	v_mul_f32_e32 v159, v159, v199
	v_mul_f32_e32 v96, v2, v156
	v_cvt_pk_bf16_f32 v96, v96, s0
	v_mul_f32_e32 v97, v3, v157
	v_cvt_pk_bf16_f32 v97, v97, s0
	v_mul_f32_e32 v98, v4, v158
	v_cvt_pk_bf16_f32 v98, v98, s0
	v_mul_f32_e32 v99, v5, v159
	v_cvt_pk_bf16_f32 v99, v99, s0
	ds_write_b16 v19, v96 offset:14
	ds_write_b16 v19, v97 offset:286
	ds_write_b16 v19, v98 offset:558
	ds_write_b16 v19, v99 offset:830
	v_fmamk_f32 v200, v200, 0x3b800000, v216
	v_cmp_gt_f32_e32 vcc, s69, v200
	v_mul_f32_e32 v96, 0x4f800000, v200
	s_nop 0
	v_cndmask_b32_e32 v200, v200, v96, vcc
	v_sqrt_f32_e32 v96, v200
	s_nop 0
	v_add_u32_e32 v97, -1, v96
	v_fma_f32 v98, -v97, v96, v200
	v_cmp_ge_f32_e64 s[0:1], 0, v98
	v_add_u32_e32 v98, 1, v96
	s_nop 0
	v_cndmask_b32_e64 v97, v96, v97, s[0:1]
	v_fma_f32 v96, -v98, v96, v200
	v_cmp_lt_f32_e64 s[0:1], 0, v96
	s_nop 1
	v_cndmask_b32_e64 v96, v97, v98, s[0:1]
	v_mul_f32_e32 v97, 0x37800000, v96
	v_cndmask_b32_e32 v96, v96, v97, vcc
	v_cmp_class_f32_e32 vcc, v200, v217
	s_nop 1
	v_cndmask_b32_e32 v200, v96, v200, vcc
	v_div_scale_f32 v96, s[0:1], v200, v200, 1.0
	v_rcp_f32_e32 v97, v96
	s_nop 0
	v_fma_f32 v98, -v96, v97, 1.0
	v_fmac_f32_e32 v97, v98, v97
	v_div_scale_f32 v98, vcc, 1.0, v200, 1.0
	v_mul_f32_e32 v99, v98, v97
	v_fma_f32 v100, -v96, v99, v98
	v_fmac_f32_e32 v99, v100, v97
	v_fma_f32 v96, -v96, v99, v98
; __device__ __forceinline__ unsigned cvtpk_s(float lo, float hi) { typedef __bf16 bf16x2_t __attribute__((ext_vector_type(2))); f32x2 v = {lo, hi}; bf16x2_t b = __builtin_convertvector(v, bf16x2_t); return __builtin_bit_cast(unsigned, b); }
; __device__ __forceinline__ void sg_unit(const Params& P, int l, int chunk, char* shm, float* ssb) {
;     ...
;         const float rstd = 1.f / sqrtf(wave_sum((sq[0] + sq[1]) + (sq[2] + sq[3])) * (1.f / 256.f) + LN_EPS);
;         v = v * rstd * g4;
; #pragma unroll
;         for (int j = 0; j < 4; ++j) vt[(4 * lane + j) * SG_VT_PITCH + q] = (bf16_t)(at::cvtpk_s(v[j], 0.f) & 0xffffu);
	v_div_fmas_f32 v96, v96, v97, v99
	v_div_fixup_f32 v200, v96, v200, 1.0
	v_mul_f32_e32 v160, v160, v200
	v_mul_f32_e32 v161, v161, v200
	v_mul_f32_e32 v162, v162, v200
	v_mul_f32_e32 v163, v163, v200
	v_mul_f32_e32 v96, v2, v160
	v_cvt_pk_bf16_f32 v96, v96, s0
	v_mul_f32_e32 v97, v3, v161
	v_cvt_pk_bf16_f32 v97, v97, s0
	v_mul_f32_e32 v98, v4, v162
	v_cvt_pk_bf16_f32 v98, v98, s0
	v_mul_f32_e32 v99, v5, v163
	v_cvt_pk_bf16_f32 v99, v99, s0
	ds_write_b16 v19, v96 offset:16
	ds_write_b16 v19, v97 offset:288
	ds_write_b16 v19, v98 offset:560
	ds_write_b16 v19, v99 offset:832
	v_fmamk_f32 v201, v201, 0x3b800000, v216
	v_cmp_gt_f32_e32 vcc, s69, v201
	v_mul_f32_e32 v96, 0x4f800000, v201
	s_nop 0
	v_cndmask_b32_e32 v201, v201, v96, vcc
	v_sqrt_f32_e32 v96, v201
	s_nop 0
	v_add_u32_e32 v97, -1, v96
	v_fma_f32 v98, -v97, v96, v201
	v_cmp_ge_f32_e64 s[0:1], 0, v98
	v_add_u32_e32 v98, 1, v96
	s_nop 0
	v_cndmask_b32_e64 v97, v96, v97, s[0:1]
	v_fma_f32 v96, -v98, v96, v201
	v_cmp_lt_f32_e64 s[0:1], 0, v96
	s_nop 1
	v_cndmask_b32_e64 v96, v97, v98, s[0:1]
	v_mul_f32_e32 v97, 0x37800000, v96
	v_cndmask_b32_e32 v96, v96, v97, vcc
	v_cmp_class_f32_e32 vcc, v201, v217
	s_nop 1
	v_cndmask_b32_e32 v201, v96, v201, vcc
	v_div_scale_f32 v96, s[0:1], v201, v201, 1.0
	v_rcp_f32_e32 v97, v96
	s_nop 0
	v_fma_f32 v98, -v96, v97, 1.0
	v_fmac_f32_e32 v97, v98, v97
	v_div_scale_f32 v98, vcc, 1.0, v201, 1.0
	v_mul_f32_e32 v99, v98, v97
	v_fma_f32 v100, -v96, v99, v98
	v_fmac_f32_e32 v99, v100, v97
	v_fma_f32 v96, -v96, v99, v98
	v_div_fmas_f32 v96, v96, v97, v99
	v_div_fixup_f32 v201, v96, v201, 1.0
	v_mul_f32_e32 v164, v164, v201
	v_mul_f32_e32 v165, v165, v201
	v_mul_f32_e32 v166, v166, v201
	v_mul_f32_e32 v167, v167, v201
	v_mul_f32_e32 v96, v2, v164
	v_cvt_pk_bf16_f32 v96, v96, s0
	v_mul_f32_e32 v97, v3, v165
	v_cvt_pk_bf16_f32 v97, v97, s0
	v_mul_f32_e32 v98, v4, v166
	v_cvt_pk_bf16_f32 v98, v98, s0
	v_mul_f32_e32 v99, v5, v167
	v_cvt_pk_bf16_f32 v99, v99, s0
	ds_write_b16 v19, v96 offset:18
	ds_write_b16 v19, v97 offset:290
	ds_write_b16 v19, v98 offset:562
	ds_write_b16 v19, v99 offset:834
	v_fmamk_f32 v202, v202, 0x3b800000, v216
	v_cmp_gt_f32_e32 vcc, s69, v202
	v_mul_f32_e32 v96, 0x4f800000, v202
	s_nop 0
	v_cndmask_b32_e32 v202, v202, v96, vcc
	v_sqrt_f32_e32 v96, v202
	s_nop 0
	v_add_u32_e32 v97, -1, v96
	v_fma_f32 v98, -v97, v96, v202
	v_cmp_ge_f32_e64 s[0:1], 0, v98
	v_add_u32_e32 v98, 1, v96
	s_nop 0
	v_cndmask_b32_e64 v97, v96, v97, s[0:1]
	v_fma_f32 v96, -v98, v96, v202
	v_cmp_lt_f32_e64 s[0:1], 0, v96
	s_nop 1
	v_cndmask_b32_e64 v96, v97, v98, s[0:1]
	v_mul_f32_e32 v97, 0x37800000, v96
	v_cndmask_b32_e32 v96, v96, v97, vcc
	v_cmp_class_f32_e32 vcc, v202, v217
	s_nop 1
	v_cndmask_b32_e32 v202, v96, v202, vcc
	v_div_scale_f32 v96, s[0:1], v202, v202, 1.0
	v_rcp_f32_e32 v97, v96
	s_nop 0
	v_fma_f32 v98, -v96, v97, 1.0
	v_fmac_f32_e32 v97, v98, v97
	v_div_scale_f32 v98, vcc, 1.0, v202, 1.0
	v_mul_f32_e32 v99, v98, v97
	v_fma_f32 v100, -v96, v99, v98
	v_fmac_f32_e32 v99, v100, v97
	v_fma_f32 v96, -v96, v99, v98
	v_div_fmas_f32 v96, v96, v97, v99
	v_div_fixup_f32 v202, v96, v202, 1.0
	v_mul_f32_e32 v168, v168, v202
	v_mul_f32_e32 v169, v169, v202
	v_mul_f32_e32 v170, v170, v202
	v_mul_f32_e32 v171, v171, v202
	v_mul_f32_e32 v96, v2, v168
	v_cvt_pk_bf16_f32 v96, v96, s0
	v_mul_f32_e32 v97, v3, v169
	v_cvt_pk_bf16_f32 v97, v97, s0
	v_mul_f32_e32 v98, v4, v170
	v_cvt_pk_bf16_f32 v98, v98, s0
	v_mul_f32_e32 v99, v5, v171
	v_cvt_pk_bf16_f32 v99, v99, s0
	ds_write_b16 v19, v96 offset:20
	ds_write_b16 v19, v97 offset:292
	ds_write_b16 v19, v98 offset:564
	ds_write_b16 v19, v99 offset:836
	v_fmamk_f32 v203, v203, 0x3b800000, v216
	v_cmp_gt_f32_e32 vcc, s69, v203
	v_mul_f32_e32 v96, 0x4f800000, v203
	s_nop 0
	v_cndmask_b32_e32 v203, v203, v96, vcc
	v_sqrt_f32_e32 v96, v203
	s_nop 0
	v_add_u32_e32 v97, -1, v96
	v_fma_f32 v98, -v97, v96, v203
	v_cmp_ge_f32_e64 s[0:1], 0, v98
	v_add_u32_e32 v98, 1, v96
	s_nop 0
	v_cndmask_b32_e64 v97, v96, v97, s[0:1]
	v_fma_f32 v96, -v98, v96, v203
	v_cmp_lt_f32_e64 s[0:1], 0, v96
	s_nop 1
	v_cndmask_b32_e64 v96, v97, v98, s[0:1]
	v_mul_f32_e32 v97, 0x37800000, v96
	v_cndmask_b32_e32 v96, v96, v97, vcc
	v_cmp_class_f32_e32 vcc, v203, v217
	s_nop 1
	v_cndmask_b32_e32 v203, v96, v203, vcc
	v_div_scale_f32 v96, s[0:1], v203, v203, 1.0
	v_rcp_f32_e32 v97, v96
	s_nop 0
	v_fma_f32 v98, -v96, v97, 1.0
	v_fmac_f32_e32 v97, v98, v97
	v_div_scale_f32 v98, vcc, 1.0, v203, 1.0
	v_mul_f32_e32 v99, v98, v97
	v_fma_f32 v100, -v96, v99, v98
	v_fmac_f32_e32 v99, v100, v97
	v_fma_f32 v96, -v96, v99, v98
	v_div_fmas_f32 v96, v96, v97, v99
	v_div_fixup_f32 v203, v96, v203, 1.0
	v_mul_f32_e32 v172, v172, v203
	v_mul_f32_e32 v173, v173, v203
	v_mul_f32_e32 v174, v174, v203
	v_mul_f32_e32 v175, v175, v203
	v_mul_f32_e32 v96, v2, v172
	v_cvt_pk_bf16_f32 v96, v96, s0
	v_mul_f32_e32 v97, v3, v173
	v_cvt_pk_bf16_f32 v97, v97, s0
	v_mul_f32_e32 v98, v4, v174
	v_cvt_pk_bf16_f32 v98, v98, s0
	v_mul_f32_e32 v99, v5, v175
	v_cvt_pk_bf16_f32 v99, v99, s0
	ds_write_b16 v19, v96 offset:22
	ds_write_b16 v19, v97 offset:294
	ds_write_b16 v19, v98 offset:566
	ds_write_b16 v19, v99 offset:838
	v_fmamk_f32 v204, v204, 0x3b800000, v216
	v_cmp_gt_f32_e32 vcc, s69, v204
	v_mul_f32_e32 v96, 0x4f800000, v204
	s_nop 0
	v_cndmask_b32_e32 v204, v204, v96, vcc
	v_sqrt_f32_e32 v96, v204
	s_nop 0
	v_add_u32_e32 v97, -1, v96
	v_fma_f32 v98, -v97, v96, v204
	v_cmp_ge_f32_e64 s[0:1], 0, v98
	v_add_u32_e32 v98, 1, v96
	s_nop 0
	v_cndmask_b32_e64 v97, v96, v97, s[0:1]
	v_fma_f32 v96, -v98, v96, v204
	v_cmp_lt_f32_e64 s[0:1], 0, v96
	s_nop 1
	v_cndmask_b32_e64 v96, v97, v98, s[0:1]
; __device__ __forceinline__ unsigned cvtpk_s(float lo, float hi) { typedef __bf16 bf16x2_t __attribute__((ext_vector_type(2))); f32x2 v = {lo, hi}; bf16x2_t b = __builtin_convertvector(v, bf16x2_t); return __builtin_bit_cast(unsigned, b); }
; __device__ __forceinline__ void sg_unit(const Params& P, int l, int chunk, char* shm, float* ssb) {
;     ...
;         v = v * rstd * g4;
; #pragma unroll
;         for (int j = 0; j < 4; ++j) vt[(4 * lane + j) * SG_VT_PITCH + q] = (bf16_t)(at::cvtpk_s(v[j], 0.f) & 0xffffu);
;     }
;     asm volatile("s_waitcnt lgkmcnt(0)\n\ts_barrier" ::: "memory");
;     ...
;     const bf16_t* Wg = Wsb + (size_t)g * 128 * 128;
; #pragma unroll
;     for (int k0 = 0; k0 < 128; k0 += 16) {
;         bf16x8 af[2], bfr[2];
; #pragma unroll
;         for (int pt = 0; pt < 2; ++pt) af[pt] = *(const bf16x8*)(Wg + (size_t)(64 * ph + 32 * pt + r32) * 128 + k0 + 8 * hi);
	v_mul_f32_e32 v97, 0x37800000, v96
	v_cndmask_b32_e32 v96, v96, v97, vcc
	v_cmp_class_f32_e32 vcc, v204, v217
	s_nop 1
	v_cndmask_b32_e32 v204, v96, v204, vcc
	v_div_scale_f32 v96, s[0:1], v204, v204, 1.0
	v_rcp_f32_e32 v97, v96
	s_nop 0
	v_fma_f32 v98, -v96, v97, 1.0
	v_fmac_f32_e32 v97, v98, v97
	v_div_scale_f32 v98, vcc, 1.0, v204, 1.0
	v_mul_f32_e32 v99, v98, v97
	v_fma_f32 v100, -v96, v99, v98
	v_fmac_f32_e32 v99, v100, v97
	v_fma_f32 v96, -v96, v99, v98
	v_div_fmas_f32 v96, v96, v97, v99
	v_div_fixup_f32 v204, v96, v204, 1.0
	v_mul_f32_e32 v176, v176, v204
	v_mul_f32_e32 v177, v177, v204
	v_mul_f32_e32 v178, v178, v204
	v_mul_f32_e32 v179, v179, v204
	v_mul_f32_e32 v96, v2, v176
	v_cvt_pk_bf16_f32 v96, v96, s0
	v_mul_f32_e32 v97, v3, v177
	v_cvt_pk_bf16_f32 v97, v97, s0
	v_mul_f32_e32 v98, v4, v178
	v_cvt_pk_bf16_f32 v98, v98, s0
	v_mul_f32_e32 v99, v5, v179
	v_cvt_pk_bf16_f32 v99, v99, s0
	ds_write_b16 v19, v96 offset:24
	ds_write_b16 v19, v97 offset:296
	ds_write_b16 v19, v98 offset:568
	ds_write_b16 v19, v99 offset:840
	v_fmamk_f32 v205, v205, 0x3b800000, v216
	v_cmp_gt_f32_e32 vcc, s69, v205
	v_mul_f32_e32 v96, 0x4f800000, v205
	s_nop 0
	v_cndmask_b32_e32 v205, v205, v96, vcc
	v_sqrt_f32_e32 v96, v205
	s_nop 0
	v_add_u32_e32 v97, -1, v96
	v_fma_f32 v98, -v97, v96, v205
	v_cmp_ge_f32_e64 s[0:1], 0, v98
	v_add_u32_e32 v98, 1, v96
	s_nop 0
	v_cndmask_b32_e64 v97, v96, v97, s[0:1]
	v_fma_f32 v96, -v98, v96, v205
	v_cmp_lt_f32_e64 s[0:1], 0, v96
	s_nop 1
	v_cndmask_b32_e64 v96, v97, v98, s[0:1]
	v_mul_f32_e32 v97, 0x37800000, v96
	v_cndmask_b32_e32 v96, v96, v97, vcc
	v_cmp_class_f32_e32 vcc, v205, v217
	s_nop 1
	v_cndmask_b32_e32 v205, v96, v205, vcc
	v_div_scale_f32 v96, s[0:1], v205, v205, 1.0
	v_rcp_f32_e32 v97, v96
	s_nop 0
	v_fma_f32 v98, -v96, v97, 1.0
	v_fmac_f32_e32 v97, v98, v97
	v_div_scale_f32 v98, vcc, 1.0, v205, 1.0
	v_mul_f32_e32 v99, v98, v97
	v_fma_f32 v100, -v96, v99, v98
	v_fmac_f32_e32 v99, v100, v97
	v_fma_f32 v96, -v96, v99, v98
	v_div_fmas_f32 v96, v96, v97, v99
	v_div_fixup_f32 v205, v96, v205, 1.0
	v_mul_f32_e32 v180, v180, v205
	v_mul_f32_e32 v181, v181, v205
	v_mul_f32_e32 v182, v182, v205
	v_mul_f32_e32 v183, v183, v205
	v_mul_f32_e32 v96, v2, v180
	v_cvt_pk_bf16_f32 v96, v96, s0
	v_mul_f32_e32 v97, v3, v181
	v_cvt_pk_bf16_f32 v97, v97, s0
	v_mul_f32_e32 v98, v4, v182
	v_cvt_pk_bf16_f32 v98, v98, s0
	v_mul_f32_e32 v99, v5, v183
	v_cvt_pk_bf16_f32 v99, v99, s0
	ds_write_b16 v19, v96 offset:26
	ds_write_b16 v19, v97 offset:298
	ds_write_b16 v19, v98 offset:570
	ds_write_b16 v19, v99 offset:842
	v_fmamk_f32 v206, v206, 0x3b800000, v216
	v_cmp_gt_f32_e32 vcc, s69, v206
	v_mul_f32_e32 v96, 0x4f800000, v206
	s_nop 0
	v_cndmask_b32_e32 v206, v206, v96, vcc
	v_sqrt_f32_e32 v96, v206
	s_nop 0
	v_add_u32_e32 v97, -1, v96
	v_fma_f32 v98, -v97, v96, v206
	v_cmp_ge_f32_e64 s[0:1], 0, v98
	v_add_u32_e32 v98, 1, v96
	s_nop 0
	v_cndmask_b32_e64 v97, v96, v97, s[0:1]
	v_fma_f32 v96, -v98, v96, v206
	v_cmp_lt_f32_e64 s[0:1], 0, v96
	s_nop 1
	v_cndmask_b32_e64 v96, v97, v98, s[0:1]
	v_mul_f32_e32 v97, 0x37800000, v96
	v_cndmask_b32_e32 v96, v96, v97, vcc
	v_cmp_class_f32_e32 vcc, v206, v217
	s_nop 1
	v_cndmask_b32_e32 v206, v96, v206, vcc
	v_div_scale_f32 v96, s[0:1], v206, v206, 1.0
	v_rcp_f32_e32 v97, v96
	s_nop 0
	v_fma_f32 v98, -v96, v97, 1.0
	v_fmac_f32_e32 v97, v98, v97
	v_div_scale_f32 v98, vcc, 1.0, v206, 1.0
	v_mul_f32_e32 v99, v98, v97
	v_fma_f32 v100, -v96, v99, v98
	v_fmac_f32_e32 v99, v100, v97
	v_fma_f32 v96, -v96, v99, v98
	v_div_fmas_f32 v96, v96, v97, v99
	v_div_fixup_f32 v206, v96, v206, 1.0
	v_mul_f32_e32 v184, v184, v206
	v_mul_f32_e32 v185, v185, v206
	v_mul_f32_e32 v186, v186, v206
	v_mul_f32_e32 v187, v187, v206
	v_mul_f32_e32 v96, v2, v184
	v_cvt_pk_bf16_f32 v96, v96, s0
	v_mul_f32_e32 v97, v3, v185
	v_cvt_pk_bf16_f32 v97, v97, s0
	v_mul_f32_e32 v98, v4, v186
	v_cvt_pk_bf16_f32 v98, v98, s0
	v_mul_f32_e32 v99, v5, v187
	v_cvt_pk_bf16_f32 v99, v99, s0
	ds_write_b16 v19, v96 offset:28
	ds_write_b16 v19, v97 offset:300
	ds_write_b16 v19, v98 offset:572
	ds_write_b16 v19, v99 offset:844
	v_fmamk_f32 v207, v207, 0x3b800000, v216
	v_cmp_gt_f32_e32 vcc, s69, v207
	v_mul_f32_e32 v96, 0x4f800000, v207
	s_nop 0
	v_cndmask_b32_e32 v207, v207, v96, vcc
	v_sqrt_f32_e32 v96, v207
	s_nop 0
	v_add_u32_e32 v97, -1, v96
	v_fma_f32 v98, -v97, v96, v207
	v_cmp_ge_f32_e64 s[0:1], 0, v98
	v_add_u32_e32 v98, 1, v96
	s_nop 0
	v_cndmask_b32_e64 v97, v96, v97, s[0:1]
	v_fma_f32 v96, -v98, v96, v207
	v_cmp_lt_f32_e64 s[0:1], 0, v96
	s_nop 1
	v_cndmask_b32_e64 v96, v97, v98, s[0:1]
	v_mul_f32_e32 v97, 0x37800000, v96
	v_cndmask_b32_e32 v96, v96, v97, vcc
	v_cmp_class_f32_e32 vcc, v207, v217
	s_nop 1
	v_cndmask_b32_e32 v207, v96, v207, vcc
	v_div_scale_f32 v96, s[0:1], v207, v207, 1.0
	v_rcp_f32_e32 v97, v96
	s_nop 0
	v_fma_f32 v98, -v96, v97, 1.0
	v_fmac_f32_e32 v97, v98, v97
	v_div_scale_f32 v98, vcc, 1.0, v207, 1.0
	v_mul_f32_e32 v99, v98, v97
	v_fma_f32 v100, -v96, v99, v98
	v_fmac_f32_e32 v99, v100, v97
	v_fma_f32 v96, -v96, v99, v98
	v_div_fmas_f32 v96, v96, v97, v99
	v_div_fixup_f32 v207, v96, v207, 1.0
	v_mul_f32_e32 v188, v188, v207
	v_mul_f32_e32 v189, v189, v207
	v_mul_f32_e32 v190, v190, v207
	v_mul_f32_e32 v191, v191, v207
	v_mul_f32_e32 v96, v2, v188
	v_cvt_pk_bf16_f32 v96, v96, s0
	v_mul_f32_e32 v97, v3, v189
	v_cvt_pk_bf16_f32 v97, v97, s0
	v_mul_f32_e32 v98, v4, v190
	v_cvt_pk_bf16_f32 v98, v98, s0
	v_mul_f32_e32 v99, v5, v191
	v_cvt_pk_bf16_f32 v99, v99, s0
	ds_write_b16 v19, v96 offset:30
	ds_write_b16 v19, v97 offset:302
	ds_write_b16 v19, v98 offset:574
	ds_write_b16 v19, v99 offset:846
	s_lshl_b32 s7, s3, 7
	s_add_u32 s10, s4, 0x200000
	s_addc_u32 s11, s5, 0
	s_ashr_i32 s4, s6, 7
	s_ashr_i32 s5, s4, 31
	s_bfe_u32 s1, s6, 0x10006
	s_lshl_b64 s[8:9], s[4:5], 15
	v_readlane_b32 s0, v252, 20
	v_and_b32_e32 v14, 31, v12
	v_lshrrev_b32_e32 v15, 5, v13
	s_add_u32 s8, s0, s8
	v_readlane_b32 s0, v252, 21
	s_addc_u32 s9, s0, s9
	v_lshlrev_b32_e32 v0, 4, v15
	v_lshlrev_b32_e32 v2, 8, v14
	v_lshl_add_u64 v[4:5], s[8:9], 0, v[0:1]
	v_lshl_or_b32 v10, s1, 14, v2
	v_mov_b32_e32 v11, v1
	s_waitcnt lgkmcnt(0)
	s_barrier
; __device__ __forceinline__ void sg_unit(const Params& P, int l, int chunk, char* shm, float* ssb) {
;     ...
;     const bf16_t* Wg = Wsb + (size_t)g * 128 * 128;
; #pragma unroll
;     for (int k0 = 0; k0 < 128; k0 += 16) {
;         bf16x8 af[2], bfr[2];
; #pragma unroll
;         for (int pt = 0; pt < 2; ++pt) af[pt] = *(const bf16x8*)(Wg + (size_t)(64 * ph + 32 * pt + r32) * 128 + k0 + 8 * hi);
; #pragma unroll
;         for (int ct = 0; ct < 2; ++ct) bfr[ct] = *(const bf16x8*)(vt + (64 * g + 32 * ct + r32) * SG_VT_PITCH + k0 + 8 * hi);
; #pragma unroll
;         for (int pt = 0; pt < 2; ++pt)
; #pragma unroll
;             for (int ct = 0; ct < 2; ++ct) acc[pt][ct] = __builtin_amdgcn_mfma_f32_32x32x16_bf16(af[pt], bfr[ct], acc[pt][ct], 0, 0, 0);
;     }
	v_lshl_add_u64 v[2:3], v[4:5], 0, v[10:11]
	v_or_b32_e32 v10, 0x2000, v10
	v_lshl_add_u64 v[4:5], v[4:5], 0, v[10:11]
	global_load_dwordx4 v[96:99], v[2:3], off
	global_load_dwordx4 v[100:103], v[4:5], off
	global_load_dwordx4 v[104:107], v[2:3], off offset:32
	global_load_dwordx4 v[108:111], v[4:5], off offset:32
	global_load_dwordx4 v[112:115], v[2:3], off offset:64
	global_load_dwordx4 v[116:119], v[4:5], off offset:64
	global_load_dwordx4 v[120:123], v[2:3], off offset:96
	global_load_dwordx4 v[124:127], v[4:5], off offset:96
	global_load_dwordx4 v[128:131], v[2:3], off offset:128
	global_load_dwordx4 v[132:135], v[4:5], off offset:128
	global_load_dwordx4 v[136:139], v[2:3], off offset:160
	global_load_dwordx4 v[140:143], v[4:5], off offset:160
	global_load_dwordx4 v[144:147], v[2:3], off offset:192
	global_load_dwordx4 v[148:151], v[4:5], off offset:192
	global_load_dwordx4 v[152:155], v[2:3], off offset:224
	global_load_dwordx4 v[156:159], v[4:5], off offset:224
	s_lshl_b32 s0, s4, 6
	v_or_b32_e32 v22, s0, v14
	s_movk_i32 s4, 0x110
	v_mul_lo_u32 v10, v22, s4
	v_add3_u32 v0, 0, v0, v10
	ds_read_b128 v[22:25], v0 offset:8704
	ds_read_b128 v[26:29], v0
	ds_read_b128 v[84:87], v0 offset:32
	s_and_b32 s4, s6, 0xffffff80
	s_ashr_i32 s5, s4, 31
	s_lshl_b64 s[4:5], s[4:5], 2
	v_readlane_b32 s6, v252, 22
	s_add_u32 s4, s6, s4
	v_readlane_b32 s6, v252, 23
	s_addc_u32 s5, s6, s5
	s_lshl_b32 s6, s1, 6
	s_or_b32 s86, s6, s7
	s_ashr_i32 s1, s0, 31
	s_lshl_b32 s2, s2, 12
	s_add_i32 s2, s2, 0
	s_lshl_b64 s[0:1], s[0:1], 1
	s_add_i32 s2, s2, 0x12000
	v_lshlrev_b32_e32 v10, 1, v14
	s_waitcnt lgkmcnt(1)
	s_waitcnt vmcnt(0)
	v_mfma_f32_32x32x16_bf16 v[66:81], v[96:99], v[26:29], 0
	v_mfma_f32_32x32x16_bf16 v[50:65], v[96:99], v[22:25], 0
	ds_read_b128 v[92:95], v0 offset:8736
	v_mfma_f32_32x32x16_bf16 v[34:49], v[100:103], v[26:29], 0
	v_mfma_f32_32x32x16_bf16 v[18:33], v[100:103], v[22:25], 0
	s_waitcnt lgkmcnt(1)
	v_mfma_f32_32x32x16_bf16 v[66:81], v[104:107], v[84:87], v[66:81]
	s_waitcnt lgkmcnt(0)
	v_mfma_f32_32x32x16_bf16 v[50:65], v[104:107], v[92:95], v[50:65]
	v_mfma_f32_32x32x16_bf16 v[34:49], v[108:111], v[84:87], v[34:49]
	v_mfma_f32_32x32x16_bf16 v[18:33], v[108:111], v[92:95], v[18:33]
	ds_read_b128 v[88:91], v0 offset:64
	ds_read_b128 v[92:95], v0 offset:8768
	s_waitcnt lgkmcnt(1)
	v_mfma_f32_32x32x16_bf16 v[66:81], v[112:115], v[88:91], v[66:81]
	s_waitcnt lgkmcnt(0)
	v_mfma_f32_32x32x16_bf16 v[50:65], v[112:115], v[92:95], v[50:65]
	v_mfma_f32_32x32x16_bf16 v[34:49], v[116:119], v[88:91], v[34:49]
	v_mfma_f32_32x32x16_bf16 v[18:33], v[116:119], v[92:95], v[18:33]
	ds_read_b128 v[88:91], v0 offset:96
	ds_read_b128 v[92:95], v0 offset:8800
	s_waitcnt lgkmcnt(1)
	v_mfma_f32_32x32x16_bf16 v[66:81], v[120:123], v[88:91], v[66:81]
	s_waitcnt lgkmcnt(0)
	v_mfma_f32_32x32x16_bf16 v[50:65], v[120:123], v[92:95], v[50:65]
	v_mfma_f32_32x32x16_bf16 v[34:49], v[124:127], v[88:91], v[34:49]
	v_mfma_f32_32x32x16_bf16 v[18:33], v[124:127], v[92:95], v[18:33]
	ds_read_b128 v[88:91], v0 offset:128
	ds_read_b128 v[92:95], v0 offset:8832
	s_waitcnt lgkmcnt(1)
	v_mfma_f32_32x32x16_bf16 v[66:81], v[128:131], v[88:91], v[66:81]
	s_waitcnt lgkmcnt(0)
	v_mfma_f32_32x32x16_bf16 v[50:65], v[128:131], v[92:95], v[50:65]
	v_mfma_f32_32x32x16_bf16 v[34:49], v[132:135], v[88:91], v[34:49]
	v_mfma_f32_32x32x16_bf16 v[18:33], v[132:135], v[92:95], v[18:33]
	ds_read_b128 v[88:91], v0 offset:160
	ds_read_b128 v[92:95], v0 offset:8864
	s_waitcnt lgkmcnt(1)
	v_mfma_f32_32x32x16_bf16 v[66:81], v[136:139], v[88:91], v[66:81]
	s_waitcnt lgkmcnt(0)
	v_mfma_f32_32x32x16_bf16 v[50:65], v[136:139], v[92:95], v[50:65]
	v_mfma_f32_32x32x16_bf16 v[34:49], v[140:143], v[88:91], v[34:49]
	v_mfma_f32_32x32x16_bf16 v[18:33], v[140:143], v[92:95], v[18:33]
	ds_read_b128 v[88:91], v0 offset:192
	ds_read_b128 v[92:95], v0 offset:8896
	s_waitcnt lgkmcnt(1)
	v_mfma_f32_32x32x16_bf16 v[66:81], v[144:147], v[88:91], v[66:81]
	s_waitcnt lgkmcnt(0)
	v_mfma_f32_32x32x16_bf16 v[50:65], v[144:147], v[92:95], v[50:65]
	s_nop 0
	v_mfma_f32_32x32x16_bf16 v[34:49], v[148:151], v[88:91], v[34:49]
	v_mfma_f32_32x32x16_bf16 v[18:33], v[148:151], v[92:95], v[18:33]
	ds_read_b128 v[84:87], v0 offset:224
	ds_read_b128 v[88:91], v0 offset:8928
	v_lshl_or_b32 v0, v15, 2, s6
	s_waitcnt lgkmcnt(1)
	v_mfma_f32_32x32x16_bf16 v[66:81], v[152:155], v[84:87], v[66:81]
	v_mfma_f32_32x32x16_bf16 v[34:49], v[156:159], v[84:87], v[34:49]
	v_or_b32_e32 v86, s7, v0
	v_readlane_b32 s6, v254, 8
	v_and_b32_e32 v87, 7, v12
	v_lshlrev_b32_e32 v12, 2, v0
	v_mul_lo_u32 v0, v86, s80
	v_readlane_b32 s7, v254, 9
	v_lshlrev_b32_e32 v14, 4, v87
	s_waitcnt lgkmcnt(0)
; __device__ __forceinline__ float bf2f(unsigned short h) { return __uint_as_float(((unsigned)h) << 16); }
; __device__ __forceinline__ int crow(int r, int hi) { return (r & 3) + 8 * (r >> 2) + 4 * hi; }
; __device__ __forceinline__ void sg_unit(const Params& P, int l, int chunk, char* shm, float* ssb) {
;     ...
;         for (int pt = 0; pt < 2; ++pt)
; #pragma unroll
;             for (int ct = 0; ct < 2; ++ct) acc[pt][ct] = __builtin_amdgcn_mfma_f32_32x32x16_bf16(af[pt], bfr[ct], acc[pt][ct], 0, 0, 0);
;     }
;     const float* bs = P.b_s + (size_t)l * 512 + g * 128;
;     float ones[16];
; #pragma unroll
;     for (int r = 0; r < 16; ++r) ones[r] = 1.0f;
; #pragma unroll
;     for (int pt = 0; pt < 2; ++pt) {
;         f32x16 o[2];
; #pragma unroll
;         for (int r = 0; r < 16; ++r) { const int p = 64 * ph + 32 * pt + at::crow(r, hi); const float bp = bs[p];
; #pragma unroll
;             for (int ct = 0; ct < 2; ++ct) { const float uu = bf2f(qkv[(size_t)(R0 + p) * DIN + C_U + 64 * g + 32 * ct + r32]); o[ct][r] = uu * (acc[pt][ct][r] + bp); } }
	v_mfma_f32_32x32x16_bf16 v[50:65], v[152:155], v[88:91], v[50:65]
	v_mov_b32_e32 v9, v1
	v_cmp_eq_u32_e32 vcc, 0, v87
	v_mov_b32_e32 v7, v1
	v_mfma_f32_32x32x16_bf16 v[18:33], v[156:159], v[88:91], v[18:33]
	v_lshl_add_u64 v[90:91], s[6:7], 0, v[0:1]
	v_lshlrev_b32_e32 v2, 9, v15
	v_lshrrev_b32_e32 v89, 3, v13
	v_lshl_add_u64 v[90:91], v[90:91], 0, s[0:1]
	v_add3_u32 v85, s2, v2, v10
	v_add_u32_e32 v88, s2, v14
	v_lshlrev_b32_e32 v2, 7, v89
	v_lshl_add_u64 v[90:91], v[90:91], 0, v[10:11]
	v_add_u32_e32 v84, v88, v2
	v_mov_b32_e32 v192, v10
	v_mov_b32_e32 v193, v1
	global_load_dwordx4 v[160:163], v12, s[4:5]
	global_load_dwordx4 v[164:167], v12, s[4:5] offset:32
	global_load_dwordx4 v[168:171], v12, s[4:5] offset:64
	global_load_dwordx4 v[172:175], v12, s[4:5] offset:96
	global_load_dwordx4 v[176:179], v12, s[4:5] offset:128
	global_load_dwordx4 v[180:183], v12, s[4:5] offset:160
	global_load_dwordx4 v[184:187], v12, s[4:5] offset:192
	global_load_dwordx4 v[188:191], v12, s[4:5] offset:224
	v_or_b32_e32 v194, 0, v86
	v_mul_lo_u32 v194, v194, s80
	v_mov_b32_e32 v195, v1
	v_lshl_add_u64 v[194:195], s[6:7], 0, v[194:195]
	v_lshl_add_u64 v[194:195], v[194:195], 0, s[0:1]
	v_lshl_add_u64 v[194:195], v[194:195], 0, v[192:193]
	global_load_ushort v96, v[194:195], off offset:1024
	global_load_ushort v97, v[194:195], off offset:1088
	v_or_b32_e32 v196, 1, v86
	v_mul_lo_u32 v196, v196, s80
	v_mov_b32_e32 v197, v1
	v_lshl_add_u64 v[196:197], s[6:7], 0, v[196:197]
	v_lshl_add_u64 v[196:197], v[196:197], 0, s[0:1]
	v_lshl_add_u64 v[196:197], v[196:197], 0, v[192:193]
	global_load_ushort v98, v[196:197], off offset:1024
	global_load_ushort v99, v[196:197], off offset:1088
	v_or_b32_e32 v194, 2, v86
	v_mul_lo_u32 v194, v194, s80
	v_mov_b32_e32 v195, v1
	v_lshl_add_u64 v[194:195], s[6:7], 0, v[194:195]
	v_lshl_add_u64 v[194:195], v[194:195], 0, s[0:1]
	v_lshl_add_u64 v[194:195], v[194:195], 0, v[192:193]
	global_load_ushort v100, v[194:195], off offset:1024
	global_load_ushort v101, v[194:195], off offset:1088
	v_or_b32_e32 v196, 3, v86
	v_mul_lo_u32 v196, v196, s80
	v_mov_b32_e32 v197, v1
	v_lshl_add_u64 v[196:197], s[6:7], 0, v[196:197]
	v_lshl_add_u64 v[196:197], v[196:197], 0, s[0:1]
	v_lshl_add_u64 v[196:197], v[196:197], 0, v[192:193]
	global_load_ushort v102, v[196:197], off offset:1024
	global_load_ushort v103, v[196:197], off offset:1088
	v_or_b32_e32 v194, 8, v86
	v_mul_lo_u32 v194, v194, s80
	v_mov_b32_e32 v195, v1
	v_lshl_add_u64 v[194:195], s[6:7], 0, v[194:195]
	v_lshl_add_u64 v[194:195], v[194:195], 0, s[0:1]
	v_lshl_add_u64 v[194:195], v[194:195], 0, v[192:193]
	global_load_ushort v104, v[194:195], off offset:1024
	global_load_ushort v105, v[194:195], off offset:1088
	v_or_b32_e32 v196, 9, v86
	v_mul_lo_u32 v196, v196, s80
	v_mov_b32_e32 v197, v1
	v_lshl_add_u64 v[196:197], s[6:7], 0, v[196:197]
	v_lshl_add_u64 v[196:197], v[196:197], 0, s[0:1]
	v_lshl_add_u64 v[196:197], v[196:197], 0, v[192:193]
	global_load_ushort v106, v[196:197], off offset:1024
	global_load_ushort v107, v[196:197], off offset:1088
	v_or_b32_e32 v194, 10, v86
	v_mul_lo_u32 v194, v194, s80
	v_mov_b32_e32 v195, v1
	v_lshl_add_u64 v[194:195], s[6:7], 0, v[194:195]
	v_lshl_add_u64 v[194:195], v[194:195], 0, s[0:1]
	v_lshl_add_u64 v[194:195], v[194:195], 0, v[192:193]
	global_load_ushort v108, v[194:195], off offset:1024
	global_load_ushort v109, v[194:195], off offset:1088
	v_or_b32_e32 v196, 11, v86
	v_mul_lo_u32 v196, v196, s80
	v_mov_b32_e32 v197, v1
	v_lshl_add_u64 v[196:197], s[6:7], 0, v[196:197]
	v_lshl_add_u64 v[196:197], v[196:197], 0, s[0:1]
	v_lshl_add_u64 v[196:197], v[196:197], 0, v[192:193]
	global_load_ushort v110, v[196:197], off offset:1024
	global_load_ushort v111, v[196:197], off offset:1088
	v_or_b32_e32 v194, 16, v86
	v_mul_lo_u32 v194, v194, s80
	v_mov_b32_e32 v195, v1
	v_lshl_add_u64 v[194:195], s[6:7], 0, v[194:195]
	v_lshl_add_u64 v[194:195], v[194:195], 0, s[0:1]
	v_lshl_add_u64 v[194:195], v[194:195], 0, v[192:193]
	global_load_ushort v112, v[194:195], off offset:1024
	global_load_ushort v113, v[194:195], off offset:1088
	v_or_b32_e32 v196, 17, v86
	v_mul_lo_u32 v196, v196, s80
	v_mov_b32_e32 v197, v1
	v_lshl_add_u64 v[196:197], s[6:7], 0, v[196:197]
	v_lshl_add_u64 v[196:197], v[196:197], 0, s[0:1]
	v_lshl_add_u64 v[196:197], v[196:197], 0, v[192:193]
	global_load_ushort v114, v[196:197], off offset:1024
	global_load_ushort v115, v[196:197], off offset:1088
	v_or_b32_e32 v194, 18, v86
	v_mul_lo_u32 v194, v194, s80
	v_mov_b32_e32 v195, v1
	v_lshl_add_u64 v[194:195], s[6:7], 0, v[194:195]
	v_lshl_add_u64 v[194:195], v[194:195], 0, s[0:1]
	v_lshl_add_u64 v[194:195], v[194:195], 0, v[192:193]
	global_load_ushort v116, v[194:195], off offset:1024
	global_load_ushort v117, v[194:195], off offset:1088
	v_or_b32_e32 v196, 19, v86
	v_mul_lo_u32 v196, v196, s80
	v_mov_b32_e32 v197, v1
	v_lshl_add_u64 v[196:197], s[6:7], 0, v[196:197]
	v_lshl_add_u64 v[196:197], v[196:197], 0, s[0:1]
	v_lshl_add_u64 v[196:197], v[196:197], 0, v[192:193]
	global_load_ushort v118, v[196:197], off offset:1024
	global_load_ushort v119, v[196:197], off offset:1088
	v_or_b32_e32 v194, 24, v86
	v_mul_lo_u32 v194, v194, s80
	v_mov_b32_e32 v195, v1
	v_lshl_add_u64 v[194:195], s[6:7], 0, v[194:195]
	v_lshl_add_u64 v[194:195], v[194:195], 0, s[0:1]
	v_lshl_add_u64 v[194:195], v[194:195], 0, v[192:193]
	global_load_ushort v120, v[194:195], off offset:1024
	global_load_ushort v121, v[194:195], off offset:1088
	v_or_b32_e32 v196, 25, v86
	v_mul_lo_u32 v196, v196, s80
	v_mov_b32_e32 v197, v1
	v_lshl_add_u64 v[196:197], s[6:7], 0, v[196:197]
	v_lshl_add_u64 v[196:197], v[196:197], 0, s[0:1]
; __device__ __forceinline__ float bf2f(unsigned short h) { return __uint_as_float(((unsigned)h) << 16); }
; __device__ __forceinline__ int crow(int r, int hi) { return (r & 3) + 8 * (r >> 2) + 4 * hi; }
; __device__ __forceinline__ void sg_unit(const Params& P, int l, int chunk, char* shm, float* ssb) {
;     ...
;         for (int r = 0; r < 16; ++r) { const int p = 64 * ph + 32 * pt + at::crow(r, hi); const float bp = bs[p];
; #pragma unroll
;             for (int ct = 0; ct < 2; ++ct) { const float uu = bf2f(qkv[(size_t)(R0 + p) * DIN + C_U + 64 * g + 32 * ct + r32]); o[ct][r] = uu * (acc[pt][ct][r] + bp); } }
	v_lshl_add_u64 v[196:197], v[196:197], 0, v[192:193]
	global_load_ushort v122, v[196:197], off offset:1024
	global_load_ushort v123, v[196:197], off offset:1088
	v_or_b32_e32 v194, 26, v86
	v_mul_lo_u32 v194, v194, s80
	v_mov_b32_e32 v195, v1
	v_lshl_add_u64 v[194:195], s[6:7], 0, v[194:195]
	v_lshl_add_u64 v[194:195], v[194:195], 0, s[0:1]
	v_lshl_add_u64 v[194:195], v[194:195], 0, v[192:193]
	global_load_ushort v124, v[194:195], off offset:1024
	global_load_ushort v125, v[194:195], off offset:1088
	v_or_b32_e32 v196, 27, v86
	v_mul_lo_u32 v196, v196, s80
	v_mov_b32_e32 v197, v1
	v_lshl_add_u64 v[196:197], s[6:7], 0, v[196:197]
	v_lshl_add_u64 v[196:197], v[196:197], 0, s[0:1]
	v_lshl_add_u64 v[196:197], v[196:197], 0, v[192:193]
	global_load_ushort v126, v[196:197], off offset:1024
	global_load_ushort v127, v[196:197], off offset:1088
	v_or_b32_e32 v194, 32, v86
	v_mul_lo_u32 v194, v194, s80
	v_mov_b32_e32 v195, v1
	v_lshl_add_u64 v[194:195], s[6:7], 0, v[194:195]
	v_lshl_add_u64 v[194:195], v[194:195], 0, s[0:1]
	v_lshl_add_u64 v[194:195], v[194:195], 0, v[192:193]
	global_load_ushort v128, v[194:195], off offset:1024
	global_load_ushort v129, v[194:195], off offset:1088
	v_or_b32_e32 v196, 33, v86
	v_mul_lo_u32 v196, v196, s80
	v_mov_b32_e32 v197, v1
	v_lshl_add_u64 v[196:197], s[6:7], 0, v[196:197]
	v_lshl_add_u64 v[196:197], v[196:197], 0, s[0:1]
	v_lshl_add_u64 v[196:197], v[196:197], 0, v[192:193]
	global_load_ushort v130, v[196:197], off offset:1024
	global_load_ushort v131, v[196:197], off offset:1088
	v_or_b32_e32 v194, 34, v86
	v_mul_lo_u32 v194, v194, s80
	v_mov_b32_e32 v195, v1
	v_lshl_add_u64 v[194:195], s[6:7], 0, v[194:195]
	v_lshl_add_u64 v[194:195], v[194:195], 0, s[0:1]
	v_lshl_add_u64 v[194:195], v[194:195], 0, v[192:193]
	global_load_ushort v132, v[194:195], off offset:1024
	global_load_ushort v133, v[194:195], off offset:1088
	v_or_b32_e32 v196, 35, v86
	v_mul_lo_u32 v196, v196, s80
	v_mov_b32_e32 v197, v1
	v_lshl_add_u64 v[196:197], s[6:7], 0, v[196:197]
	v_lshl_add_u64 v[196:197], v[196:197], 0, s[0:1]
	v_lshl_add_u64 v[196:197], v[196:197], 0, v[192:193]
	global_load_ushort v134, v[196:197], off offset:1024
	global_load_ushort v135, v[196:197], off offset:1088
	v_or_b32_e32 v194, 40, v86
	v_mul_lo_u32 v194, v194, s80
	v_mov_b32_e32 v195, v1
	v_lshl_add_u64 v[194:195], s[6:7], 0, v[194:195]
	v_lshl_add_u64 v[194:195], v[194:195], 0, s[0:1]
	v_lshl_add_u64 v[194:195], v[194:195], 0, v[192:193]
	global_load_ushort v136, v[194:195], off offset:1024
	global_load_ushort v137, v[194:195], off offset:1088
	v_or_b32_e32 v196, 41, v86
	v_mul_lo_u32 v196, v196, s80
	v_mov_b32_e32 v197, v1
	v_lshl_add_u64 v[196:197], s[6:7], 0, v[196:197]
	v_lshl_add_u64 v[196:197], v[196:197], 0, s[0:1]
	v_lshl_add_u64 v[196:197], v[196:197], 0, v[192:193]
	global_load_ushort v138, v[196:197], off offset:1024
	global_load_ushort v139, v[196:197], off offset:1088
	v_or_b32_e32 v194, 42, v86
	v_mul_lo_u32 v194, v194, s80
	v_mov_b32_e32 v195, v1
	v_lshl_add_u64 v[194:195], s[6:7], 0, v[194:195]
	v_lshl_add_u64 v[194:195], v[194:195], 0, s[0:1]
	v_lshl_add_u64 v[194:195], v[194:195], 0, v[192:193]
	global_load_ushort v140, v[194:195], off offset:1024
	global_load_ushort v141, v[194:195], off offset:1088
	v_or_b32_e32 v196, 43, v86
	v_mul_lo_u32 v196, v196, s80
	v_mov_b32_e32 v197, v1
	v_lshl_add_u64 v[196:197], s[6:7], 0, v[196:197]
	v_lshl_add_u64 v[196:197], v[196:197], 0, s[0:1]
	v_lshl_add_u64 v[196:197], v[196:197], 0, v[192:193]
	global_load_ushort v142, v[196:197], off offset:1024
	global_load_ushort v143, v[196:197], off offset:1088
	v_or_b32_e32 v194, 48, v86
	v_mul_lo_u32 v194, v194, s80
	v_mov_b32_e32 v195, v1
	v_lshl_add_u64 v[194:195], s[6:7], 0, v[194:195]
	v_lshl_add_u64 v[194:195], v[194:195], 0, s[0:1]
	v_lshl_add_u64 v[194:195], v[194:195], 0, v[192:193]
	global_load_ushort v144, v[194:195], off offset:1024
	global_load_ushort v145, v[194:195], off offset:1088
	v_or_b32_e32 v196, 49, v86
	v_mul_lo_u32 v196, v196, s80
	v_mov_b32_e32 v197, v1
	v_lshl_add_u64 v[196:197], s[6:7], 0, v[196:197]
	v_lshl_add_u64 v[196:197], v[196:197], 0, s[0:1]
	v_lshl_add_u64 v[196:197], v[196:197], 0, v[192:193]
	global_load_ushort v146, v[196:197], off offset:1024
	global_load_ushort v147, v[196:197], off offset:1088
	v_or_b32_e32 v194, 50, v86
	v_mul_lo_u32 v194, v194, s80
	v_mov_b32_e32 v195, v1
	v_lshl_add_u64 v[194:195], s[6:7], 0, v[194:195]
	v_lshl_add_u64 v[194:195], v[194:195], 0, s[0:1]
	v_lshl_add_u64 v[194:195], v[194:195], 0, v[192:193]
	global_load_ushort v148, v[194:195], off offset:1024
	global_load_ushort v149, v[194:195], off offset:1088
	v_or_b32_e32 v196, 51, v86
	v_mul_lo_u32 v196, v196, s80
	v_mov_b32_e32 v197, v1
	v_lshl_add_u64 v[196:197], s[6:7], 0, v[196:197]
	v_lshl_add_u64 v[196:197], v[196:197], 0, s[0:1]
	v_lshl_add_u64 v[196:197], v[196:197], 0, v[192:193]
	global_load_ushort v150, v[196:197], off offset:1024
	global_load_ushort v151, v[196:197], off offset:1088
	v_or_b32_e32 v194, 56, v86
	v_mul_lo_u32 v194, v194, s80
	v_mov_b32_e32 v195, v1
	v_lshl_add_u64 v[194:195], s[6:7], 0, v[194:195]
	v_lshl_add_u64 v[194:195], v[194:195], 0, s[0:1]
	v_lshl_add_u64 v[194:195], v[194:195], 0, v[192:193]
	global_load_ushort v152, v[194:195], off offset:1024
	global_load_ushort v153, v[194:195], off offset:1088
	v_or_b32_e32 v196, 57, v86
	v_mul_lo_u32 v196, v196, s80
	v_mov_b32_e32 v197, v1
	v_lshl_add_u64 v[196:197], s[6:7], 0, v[196:197]
	v_lshl_add_u64 v[196:197], v[196:197], 0, s[0:1]
	v_lshl_add_u64 v[196:197], v[196:197], 0, v[192:193]
	global_load_ushort v154, v[196:197], off offset:1024
	global_load_ushort v155, v[196:197], off offset:1088
	v_or_b32_e32 v194, 58, v86
	v_mul_lo_u32 v194, v194, s80
	v_mov_b32_e32 v195, v1
	v_lshl_add_u64 v[194:195], s[6:7], 0, v[194:195]
	v_lshl_add_u64 v[194:195], v[194:195], 0, s[0:1]
	v_lshl_add_u64 v[194:195], v[194:195], 0, v[192:193]
	global_load_ushort v156, v[194:195], off offset:1024
	global_load_ushort v157, v[194:195], off offset:1088
	v_or_b32_e32 v196, 59, v86
	v_mul_lo_u32 v196, v196, s80
	v_mov_b32_e32 v197, v1
	v_lshl_add_u64 v[196:197], s[6:7], 0, v[196:197]
	v_lshl_add_u64 v[196:197], v[196:197], 0, s[0:1]
	v_lshl_add_u64 v[196:197], v[196:197], 0, v[192:193]
	global_load_ushort v158, v[196:197], off offset:1024
	global_load_ushort v159, v[196:197], off offset:1088
	s_waitcnt vmcnt(0)
; __device__ __forceinline__ float bf2f(unsigned short h) { return __uint_as_float(((unsigned)h) << 16); }
; __device__ __forceinline__ int crow(int r, int hi) { return (r & 3) + 8 * (r >> 2) + 4 * hi; }
; __device__ __forceinline__ void sg_unit(const Params& P, int l, int chunk, char* shm, float* ssb) {
;     ...
;         for (int r = 0; r < 16; ++r) { const int p = 64 * ph + 32 * pt + at::crow(r, hi); const float bp = bs[p];
; #pragma unroll
;             for (int ct = 0; ct < 2; ++ct) { const float uu = bf2f(qkv[(size_t)(R0 + p) * DIN + C_U + 64 * g + 32 * ct + r32]); o[ct][r] = uu * (acc[pt][ct][r] + bp); } }
	v_mov_b64_e32 v[2:3], v[160:161]
	v_mov_b64_e32 v[4:5], v[162:163]
	v_mov_b32_e32 v0, v96
	v_lshlrev_b32_e32 v8, 11, v89
	v_lshlrev_b32_e32 v6, 4, v89
	v_add_f32_e32 v13, v66, v2
	v_lshlrev_b32_e32 v0, 16, v0
	v_mul_f32_e32 v13, v13, v0
	v_mov_b32_e32 v0, v97
	v_add_f32_e32 v2, v50, v2
	v_add_f32_e32 v66, v68, v4
	v_lshlrev_b32_e32 v0, 16, v0
	v_mul_f32_e32 v15, v2, v0
	v_or_b32_e32 v0, 1, v86
	v_mul_lo_u32 v0, v0, s80
	v_lshl_add_u64 v[90:91], s[6:7], 0, v[0:1]
	v_lshl_add_u64 v[90:91], v[90:91], 0, s[0:1]
	v_lshl_add_u64 v[90:91], v[90:91], 0, v[10:11]
	v_mov_b32_e32 v0, v98
	v_add_f32_e32 v2, v67, v3
	v_lshlrev_b32_e32 v0, 16, v0
	v_mul_f32_e32 v50, v2, v0
	v_mov_b32_e32 v0, v99
	v_add_f32_e32 v2, v51, v3
	v_lshlrev_b32_e32 v0, 16, v0
	v_mul_f32_e32 v51, v2, v0
	v_or_b32_e32 v0, 2, v86
	v_mul_lo_u32 v0, v0, s80
	v_lshl_add_u64 v[2:3], s[6:7], 0, v[0:1]
	v_lshl_add_u64 v[2:3], v[2:3], 0, s[0:1]
	v_lshl_add_u64 v[2:3], v[2:3], 0, v[10:11]
	v_mov_b32_e32 v0, v100
	v_lshlrev_b32_e32 v0, 16, v0
	v_mul_f32_e32 v66, v66, v0
	v_mov_b32_e32 v0, v101
	v_add_f32_e32 v2, v52, v4
	v_add_f32_e32 v4, v69, v5
	v_lshlrev_b32_e32 v0, 16, v0
	v_mul_f32_e32 v52, v2, v0
	v_or_b32_e32 v0, 3, v86
	v_mul_lo_u32 v0, v0, s80
	v_lshl_add_u64 v[2:3], s[6:7], 0, v[0:1]
	v_lshl_add_u64 v[2:3], v[2:3], 0, s[0:1]
	v_lshl_add_u64 v[2:3], v[2:3], 0, v[10:11]
	v_mov_b32_e32 v0, v102
	v_lshlrev_b32_e32 v0, 16, v0
	v_mul_f32_e32 v67, v4, v0
	v_mov_b32_e32 v0, v103
	v_add_f32_e32 v2, v53, v5
	v_lshlrev_b32_e32 v0, 16, v0
	v_mul_f32_e32 v53, v2, v0
	v_or_b32_e32 v0, 8, v86
	v_mul_lo_u32 v0, v0, s80
	v_lshl_add_u64 v[68:69], s[6:7], 0, v[0:1]
	v_lshl_add_u64 v[68:69], v[68:69], 0, s[0:1]
	v_lshl_add_u64 v[90:91], v[68:69], 0, v[10:11]
	v_mov_b64_e32 v[2:3], v[164:165]
	v_mov_b64_e32 v[4:5], v[166:167]
	v_mov_b32_e32 v0, v104
	v_add_f32_e32 v68, v70, v2
	v_lshlrev_b32_e32 v0, 16, v0
	v_mul_f32_e32 v68, v68, v0
	v_mov_b32_e32 v0, v105
	v_add_f32_e32 v2, v54, v2
	v_add_f32_e32 v70, v72, v4
	v_lshlrev_b32_e32 v0, 16, v0
	v_mul_f32_e32 v54, v2, v0
	v_or_b32_e32 v0, 9, v86
	v_mul_lo_u32 v0, v0, s80
	v_lshl_add_u64 v[90:91], s[6:7], 0, v[0:1]
	v_lshl_add_u64 v[90:91], v[90:91], 0, s[0:1]
	v_lshl_add_u64 v[90:91], v[90:91], 0, v[10:11]
	v_mov_b32_e32 v0, v106
	v_add_f32_e32 v2, v71, v3
	v_lshlrev_b32_e32 v0, 16, v0
	v_mul_f32_e32 v69, v2, v0
	v_mov_b32_e32 v0, v107
	v_add_f32_e32 v2, v55, v3
	v_lshlrev_b32_e32 v0, 16, v0
	v_mul_f32_e32 v55, v2, v0
	v_or_b32_e32 v0, 10, v86
	v_mul_lo_u32 v0, v0, s80
	v_lshl_add_u64 v[2:3], s[6:7], 0, v[0:1]
	v_lshl_add_u64 v[2:3], v[2:3], 0, s[0:1]
	v_lshl_add_u64 v[2:3], v[2:3], 0, v[10:11]
	v_mov_b32_e32 v0, v108
	v_lshlrev_b32_e32 v0, 16, v0
	v_mul_f32_e32 v70, v70, v0
	v_mov_b32_e32 v0, v109
	v_add_f32_e32 v2, v56, v4
	v_add_f32_e32 v4, v73, v5
	v_lshlrev_b32_e32 v0, 16, v0
	v_mul_f32_e32 v56, v2, v0
	v_or_b32_e32 v0, 11, v86
	v_mul_lo_u32 v0, v0, s80
	v_lshl_add_u64 v[2:3], s[6:7], 0, v[0:1]
	v_lshl_add_u64 v[2:3], v[2:3], 0, s[0:1]
	v_lshl_add_u64 v[2:3], v[2:3], 0, v[10:11]
	v_mov_b32_e32 v0, v110
	v_lshlrev_b32_e32 v0, 16, v0
	v_mul_f32_e32 v71, v4, v0
	v_mov_b32_e32 v0, v111
	v_add_f32_e32 v2, v57, v5
	v_lshlrev_b32_e32 v0, 16, v0
	v_mul_f32_e32 v57, v2, v0
	v_or_b32_e32 v0, 16, v86
	v_mul_lo_u32 v0, v0, s80
	v_lshl_add_u64 v[72:73], s[6:7], 0, v[0:1]
	v_lshl_add_u64 v[72:73], v[72:73], 0, s[0:1]
	v_lshl_add_u64 v[90:91], v[72:73], 0, v[10:11]
	v_mov_b64_e32 v[2:3], v[168:169]
	v_mov_b64_e32 v[4:5], v[170:171]
	v_mov_b32_e32 v0, v112
	v_add_f32_e32 v72, v74, v2
	v_lshlrev_b32_e32 v0, 16, v0
	v_mul_f32_e32 v72, v72, v0
	v_mov_b32_e32 v0, v113
	v_add_f32_e32 v2, v58, v2
	v_add_f32_e32 v74, v76, v4
	v_lshlrev_b32_e32 v0, 16, v0
	v_mul_f32_e32 v58, v2, v0
	v_or_b32_e32 v0, 17, v86
	v_mul_lo_u32 v0, v0, s80
	v_lshl_add_u64 v[90:91], s[6:7], 0, v[0:1]
	v_lshl_add_u64 v[90:91], v[90:91], 0, s[0:1]
	v_lshl_add_u64 v[90:91], v[90:91], 0, v[10:11]
	v_mov_b32_e32 v0, v114
	v_add_f32_e32 v2, v75, v3
	v_lshlrev_b32_e32 v0, 16, v0
	v_mul_f32_e32 v73, v2, v0
	v_mov_b32_e32 v0, v115
	v_add_f32_e32 v2, v59, v3
	v_lshlrev_b32_e32 v0, 16, v0
	v_mul_f32_e32 v59, v2, v0
	v_or_b32_e32 v0, 18, v86
	v_mul_lo_u32 v0, v0, s80
	v_lshl_add_u64 v[2:3], s[6:7], 0, v[0:1]
	v_lshl_add_u64 v[2:3], v[2:3], 0, s[0:1]
	v_lshl_add_u64 v[2:3], v[2:3], 0, v[10:11]
	v_mov_b32_e32 v0, v116
	v_lshlrev_b32_e32 v0, 16, v0
	v_mul_f32_e32 v74, v74, v0
	v_mov_b32_e32 v0, v117
	v_add_f32_e32 v2, v60, v4
	v_add_f32_e32 v4, v77, v5
	v_lshlrev_b32_e32 v0, 16, v0
	v_mul_f32_e32 v60, v2, v0
	v_or_b32_e32 v0, 19, v86
	v_mul_lo_u32 v0, v0, s80
	v_lshl_add_u64 v[2:3], s[6:7], 0, v[0:1]
	v_lshl_add_u64 v[2:3], v[2:3], 0, s[0:1]
	v_lshl_add_u64 v[2:3], v[2:3], 0, v[10:11]
	v_mov_b32_e32 v0, v118
	v_lshlrev_b32_e32 v0, 16, v0
	v_mul_f32_e32 v75, v4, v0
	v_mov_b32_e32 v0, v119
	v_add_f32_e32 v2, v61, v5
	v_lshlrev_b32_e32 v0, 16, v0
	v_mul_f32_e32 v61, v2, v0
	v_or_b32_e32 v0, 24, v86
	v_mul_lo_u32 v0, v0, s80
	v_lshl_add_u64 v[76:77], s[6:7], 0, v[0:1]
	v_lshl_add_u64 v[76:77], v[76:77], 0, s[0:1]
	v_lshl_add_u64 v[90:91], v[76:77], 0, v[10:11]
; __device__ __forceinline__ float bf2f(unsigned short h) { return __uint_as_float(((unsigned)h) << 16); }
; __device__ __forceinline__ int crow(int r, int hi) { return (r & 3) + 8 * (r >> 2) + 4 * hi; }
; __device__ __forceinline__ unsigned cvtpk_s(float lo, float hi) { typedef __bf16 bf16x2_t __attribute__((ext_vector_type(2))); f32x2 v = {lo, hi}; bf16x2_t b = __builtin_convertvector(v, bf16x2_t); return __builtin_bit_cast(unsigned, b); }
; __device__ __forceinline__ void store_tile(const f32x16* o, const float* rli, bf16_t* stg, bf16_t* Ow, int pitch, float* ss, int lane, int r32, int hi) {
; #pragma unroll
;     for (int r = 0; r < 16; ++r) { const int orow = crow(r, hi);
; #pragma unroll
;         for (int d0 = 0; d0 < 2; ++d0) stg[orow * 64 + d0 * 32 + r32] = (bf16_t)(cvtpk_s(o[d0][r] * rli[r], 0.f) & 0xffffu); }
;     asm volatile("s_waitcnt lgkmcnt(0)" ::: "memory");
; #pragma unroll
;     for (int i = 0; i < 4; ++i) { const int row = i * 8 + (lane >> 3), ch = lane & 7; const u32x4 v = *(const u32x4*)(stg + row * 64 + ch * 8);
;         { const bf16_t* gp_ = Ow + (long)row * pitch + ch * 8; asm volatile("global_store_dwordx4 %0, %1, off sc0 sc1\n\ts_nop 1" :: "v"(gp_), "v"(v) : "memory"); }
;         float s = 0.f;
; #pragma unroll
;         for (int j = 0; j < 4; ++j) { const float a = __uint_as_float(v[j] << 16), b = __uint_as_float(v[j] & 0xffff0000u); s += a * a + b * b; }
;         s += __shfl_xor(s, 1); s += __shfl_xor(s, 2); s += __shfl_xor(s, 4);
;         if (ch == 0) atomicAdd(ss + (long)row * 4, s); }
; __device__ __forceinline__ void sg_unit(const Params& P, int l, int chunk, char* shm, float* ssb) {
;     ...
;         for (int r = 0; r < 16; ++r) { const int p = 64 * ph + 32 * pt + at::crow(r, hi); const float bp = bs[p];
; #pragma unroll
;             for (int ct = 0; ct < 2; ++ct) { const float uu = bf2f(qkv[(size_t)(R0 + p) * DIN + C_U + 64 * g + 32 * ct + r32]); o[ct][r] = uu * (acc[pt][ct][r] + bp); } }
;         const int prow = R0 + 64 * ph + 32 * pt;
;         at::store_tile(o, ones, (bf16_t*)(shm + SG_STAGE) + wid * 2048, omix + (size_t)prow * DM + 384 + 64 * g, DM, ssb + (size_t)prow * 4 + 1, lane, r32, hi);
	v_mov_b64_e32 v[2:3], v[172:173]
	v_mov_b64_e32 v[4:5], v[174:175]
	v_mov_b32_e32 v0, v120
	v_add_f32_e32 v76, v78, v2
	v_lshlrev_b32_e32 v0, 16, v0
	v_mul_f32_e32 v76, v76, v0
	v_mov_b32_e32 v0, v121
	v_add_f32_e32 v2, v62, v2
	v_add_f32_e32 v62, v79, v3
	v_add_f32_e32 v3, v63, v3
	v_add_f32_e32 v63, v80, v4
	v_add_f32_e32 v4, v64, v4
	v_lshlrev_b32_e32 v0, 16, v0
	v_mul_f32_e32 v2, v2, v0
	v_or_b32_e32 v0, 25, v86
	v_mul_lo_u32 v0, v0, s80
	v_lshl_add_u64 v[90:91], s[6:7], 0, v[0:1]
	v_lshl_add_u64 v[90:91], v[90:91], 0, s[0:1]
	v_lshl_add_u64 v[90:91], v[90:91], 0, v[10:11]
	v_mov_b32_e32 v0, v122
	v_cvt_pk_bf16_f32 v2, v2, s0
	ds_write_b16 v85, v2 offset:3136
	v_lshlrev_b32_e32 v0, 16, v0
	v_mul_f32_e32 v62, v62, v0
	v_mov_b32_e32 v0, v123
	v_cvt_pk_bf16_f32 v2, v62, s0
	ds_write_b16 v85, v2 offset:3200
	v_lshlrev_b32_e32 v0, 16, v0
	v_mul_f32_e32 v3, v3, v0
	v_or_b32_e32 v0, 26, v86
	v_mul_lo_u32 v0, v0, s80
	v_lshl_add_u64 v[78:79], s[6:7], 0, v[0:1]
	v_lshl_add_u64 v[78:79], v[78:79], 0, s[0:1]
	v_lshl_add_u64 v[78:79], v[78:79], 0, v[10:11]
	v_mov_b32_e32 v0, v124
	v_cvt_pk_bf16_f32 v2, v3, s0
	ds_write_b16 v85, v2 offset:3264
	v_lshlrev_b32_e32 v0, 16, v0
	v_mul_f32_e32 v63, v63, v0
	v_mov_b32_e32 v0, v125
	v_cvt_pk_bf16_f32 v2, v63, s0
	ds_write_b16 v85, v2 offset:3328
	v_lshlrev_b32_e32 v0, 16, v0
	v_mul_f32_e32 v4, v4, v0
	v_or_b32_e32 v0, 27, v86
	v_mul_lo_u32 v0, v0, s80
	v_lshl_add_u64 v[78:79], s[6:7], 0, v[0:1]
	v_lshl_add_u64 v[78:79], v[78:79], 0, s[0:1]
	v_lshl_add_u64 v[78:79], v[78:79], 0, v[10:11]
	v_mov_b32_e32 v0, v126
	v_add_f32_e32 v11, v81, v5
	v_add_f32_e32 v5, v65, v5
	s_lshl_b64 s[6:7], s[86:87], 11
	v_cvt_pk_bf16_f32 v2, v4, s0
	s_add_u32 s2, s76, s6
	ds_write_b16 v85, v2 offset:3392
	s_addc_u32 s6, s77, s7
	s_add_u32 s8, s2, s0
	s_addc_u32 s9, s6, s1
	s_lshl_b64 s[6:7], s[86:87], 4
	s_add_u32 s6, s10, s6
	s_addc_u32 s7, s11, s7
	v_lshlrev_b32_e32 v0, 16, v0
	v_mul_f32_e32 v0, v11, v0
	v_mov_b32_e32 v11, v127
	v_cvt_pk_bf16_f32 v0, v0, s0
	ds_write_b16 v85, v0 offset:3456
	v_lshlrev_b32_e32 v11, 16, v11
	v_mul_f32_e32 v5, v5, v11
	v_cvt_pk_bf16_f32 v11, v13, s0
	ds_write_b16 v85, v11
	v_cvt_pk_bf16_f32 v11, v15, s0
	ds_write_b16 v85, v11 offset:64
	v_cvt_pk_bf16_f32 v11, v50, s0
	ds_write_b16 v85, v11 offset:128
	v_cvt_pk_bf16_f32 v11, v51, s0
	ds_write_b16 v85, v11 offset:192
	v_cvt_pk_bf16_f32 v11, v66, s0
	ds_write_b16 v85, v11 offset:256
	v_cvt_pk_bf16_f32 v11, v52, s0
	ds_write_b16 v85, v11 offset:320
	v_cvt_pk_bf16_f32 v11, v67, s0
	ds_write_b16 v85, v11 offset:384
	v_cvt_pk_bf16_f32 v11, v53, s0
	ds_write_b16 v85, v11 offset:448
	v_cvt_pk_bf16_f32 v11, v68, s0
	ds_write_b16 v85, v11 offset:1024
	v_cvt_pk_bf16_f32 v11, v54, s0
	ds_write_b16 v85, v11 offset:1088
	v_cvt_pk_bf16_f32 v11, v69, s0
	ds_write_b16 v85, v11 offset:1152
	v_cvt_pk_bf16_f32 v11, v55, s0
	ds_write_b16 v85, v11 offset:1216
	v_cvt_pk_bf16_f32 v11, v70, s0
	ds_write_b16 v85, v11 offset:1280
	v_cvt_pk_bf16_f32 v11, v56, s0
	ds_write_b16 v85, v11 offset:1344
	v_cvt_pk_bf16_f32 v11, v71, s0
	ds_write_b16 v85, v11 offset:1408
	v_cvt_pk_bf16_f32 v11, v57, s0
	ds_write_b16 v85, v11 offset:1472
	v_cvt_pk_bf16_f32 v11, v72, s0
	ds_write_b16 v85, v11 offset:2048
	v_cvt_pk_bf16_f32 v11, v58, s0
	ds_write_b16 v85, v11 offset:2112
	v_cvt_pk_bf16_f32 v11, v73, s0
	ds_write_b16 v85, v11 offset:2176
	v_cvt_pk_bf16_f32 v11, v59, s0
	ds_write_b16 v85, v11 offset:2240
	v_cvt_pk_bf16_f32 v11, v74, s0
	ds_write_b16 v85, v11 offset:2304
	v_cvt_pk_bf16_f32 v11, v60, s0
	ds_write_b16 v85, v11 offset:2368
	v_cvt_pk_bf16_f32 v11, v75, s0
	ds_write_b16 v85, v11 offset:2432
	v_cvt_pk_bf16_f32 v11, v61, s0
	ds_write_b16 v85, v11 offset:2496
	v_cvt_pk_bf16_f32 v11, v76, s0
	v_cvt_pk_bf16_f32 v0, v5, s0
	ds_write_b16 v85, v11 offset:3072
	ds_write_b16 v85, v0 offset:3520
	s_waitcnt lgkmcnt(0)
	ds_read_b128 v[50:53], v84
	v_mov_b32_e32 v15, v1
	v_lshl_add_u64 v[2:3], s[8:9], 0, v[14:15]
	s_mov_b64 s[8:9], 0x12e40300
	v_lshl_add_u64 v[2:3], v[2:3], 0, s[8:9]
	v_lshl_add_u64 v[4:5], v[2:3], 0, v[8:9]
	s_waitcnt lgkmcnt(0)
	global_store_dwordx4 v[4:5], v[50:53], off sc0 sc1
	s_nop 1
	v_and_b32_e32 v4, 0xffff0000, v50
	v_lshlrev_b32_e32 v0, 16, v50
	v_mul_f32_e32 v4, v4, v4
	v_and_b32_e32 v5, 0xffff0000, v51
	v_fmac_f32_e32 v4, v0, v0
	v_lshlrev_b32_e32 v0, 16, v51
	v_mul_f32_e32 v5, v5, v5
	v_fmac_f32_e32 v5, v0, v0
	v_add_f32_e32 v0, v4, v5
	v_and_b32_e32 v5, 0xffff0000, v52
	v_lshlrev_b32_e32 v4, 16, v52
	v_mul_f32_e32 v5, v5, v5
	v_fmac_f32_e32 v5, v4, v4
	v_add_f32_e32 v0, v5, v0
	v_and_b32_e32 v5, 0xffff0000, v53
	v_lshlrev_b32_e32 v4, 16, v53
	v_mul_f32_e32 v5, v5, v5
	v_fmac_f32_e32 v5, v4, v4
	v_add_f32_e32 v0, v5, v0
	ds_bpermute_b32 v4, v17, v0
	s_waitcnt lgkmcnt(0)
	v_add_f32_e32 v0, v0, v4
	ds_bpermute_b32 v4, v83, v0
	s_waitcnt lgkmcnt(0)
	v_add_f32_e32 v0, v0, v4
	ds_bpermute_b32 v4, v82, v0
	s_and_saveexec_b64 s[8:9], vcc
	s_cbranch_execz .LBB0_562
	v_lshl_add_u64 v[14:15], s[6:7], 0, v[6:7]
	s_waitcnt lgkmcnt(0)
	v_add_f32_e32 v0, v0, v4
	flat_atomic_add_f32 v[14:15], v0 offset:4
